# NA context tiles: same unit-level software pipelining as the SWA tiles (QK of unit u+1, exp/sum/cvt of unit u, PV of unit u-1 interleaved)
# speedup vs baseline: 1.0089x; 1.0022x over previous
; #define LAS __attribute__((address_space(3)))
;     const int l15 = lane & 15, g = lane >> 4, q4 = l15 >> 2;
;     const LAS unsigned char* kb0 = Kt + l15 * 128;
;     const int kx0 = ((g) ^ (l15 & 7)) << 4, kx1 = ((4 + g) ^ (l15 & 7)) << 4;
;     const LAS unsigned char* vrow = Vt + (4 * g + q4) * 128 + (lane & 3) * 8;
;     const int swz = (2 * (g & 1) + (q4 >> 1)) & 3;
; __device__ __forceinline__ void na_phase(LAS unsigned char* lds, const bf16_t* Q, const bf16_t* K, const bf16_t* V, bf16_t* Ob, const float* rpb, float negb) {
;     ...
;         if (!isctx) { b = item >> 8; hp = (item >> 5) & 7; rq = item & 31; } else { const int j = item - NA_ITEMS_LAT; b = j >> 3; hp = j & 7; rq = 0; }
;         const int hh = w >> 2, head = 2 * hp + hh;
;         const size_t ctx0 = (size_t)(MLAT + b * NCTX), lat0 = (size_t)(b * SEQ);
;         const int kr_lo = min(max(4 * rq - 4, 0), 120), kr_hi = min(max(4 * rq - 1, 0), 120) + 8;
;         const int NT = 4 + (isctx ? 0 : kr_hi - kr_lo);
;         const DmaLane dl = dma_lane(DM, hp * 128, w, lane);
;     ...
;         dma_tile<2>(lds, K, V, NA_ROW0(0), DM, dl, w);
;         dma_tile<2>(lds + NA_BUF, K, V, NA_ROW0(1), DM, dl, w);
;         dma_tile<2>(lds + 2 * NA_BUF, K, V, NA_ROW0(2), DM, dl, w);
;         for (int i = tid; i < 2 * 465; i += 512) { const int h2 = i / 465, e = i - h2 * 465; tab[h2 * 512 + e] = rpb[(2 * hp + h2) * 465 + e] * LOG2E; }
;         const int r = 4 * rq + (w & 3);
;         const size_t qrow0 = isctx ? (size_t)(MLAT + b * NCTX + (w & 3) * 64) : (size_t)(b * SEQ + r * 64);
;         bf16x8 qf[4][2];
; #pragma unroll
;         for (int grp = 0; grp < 4; ++grp)
; #pragma unroll
;             for (int ds = 0; ds < 2; ++ds) qf[grp][ds] = *(const bf16x8*)(Q + (qrow0 + 16 * grp + l15) * DM + head * 64 + 32 * ds + 8 * g);
;         f32x4 O[4][4]; float ls[4];
; #pragma unroll
;         for (int grp = 0; grp < 4; ++grp) { ls[grp] = 0.f;
; #pragma unroll
;             for (int db = 0; db < 4; ++db) O[grp][db] = (f32x4){0.f, 0.f, 0.f, 0.f}; }
;         const int r0w = min(max(r - 4, 0), 120);
;         drain_wait();
;         for (int t = 0; t < 4; ++t) {
;             dma_tile<2>(lds + ((t + 3) & 3) * NA_BUF, K, V, NA_ROW0(t + 3), DM, dl, w);
;             const LAS unsigned char* buf = lds + (t & 3) * NA_BUF;
;             full_tile<0, 1, 2>(O, ls, qf, negb, buf + hh * 8192, buf + 2 * 8192 + hh * 8192, lane, 0);
.LBB0_377:
	s_or_b64 exec, exec, s[96:97]
	v_sub_u32_e64 v4, s68, 1 clamp
	s_lshl_b32 s61, s6, 13
	v_readfirstlane_b32 s6, v4
	s_max_u32 s60, s68, 4
	s_min_u32 s6, s6, 0x78
	s_lshl_b32 s7, s7, 1
	v_readlane_b32 s59, v240, 49
	s_sub_i32 s6, s6, s60
	s_add_i32 s59, s7, s59
	s_add_i32 s66, s6, 16
	s_and_b64 s[6:7], exec, s[0:1]
	s_mov_b32 s33, s93
	s_cselect_b32 s93, 4, s66
	s_or_b32 s6, s68, s2
	v_readlane_b32 s7, v240, 48
	s_lshl_b32 s66, s6, 6
	s_or_b32 s7, s82, s7
	s_or_b32 s66, s61, s66
	s_and_b64 s[0:1], exec, s[0:1]
	s_cselect_b32 s0, s7, s66
	v_or_b32_e32 v154, s0, v199
	s_lshl_b32 s0, s59, 6
	s_ashr_i32 s1, s0, 31
	v_lshl_add_u64 v[28:29], s[0:1], 1, v[112:113]
	v_lshlrev_b64 v[122:123], 11, v[154:155]
	v_lshl_add_u64 v[8:9], v[28:29], 0, v[122:123]
	global_load_dwordx4 v[4:7], v[8:9], off
	s_nop 0
	global_load_dwordx4 v[8:11], v[8:9], off offset:64
	s_max_i32 s97, s6, 4
	s_or_b32 s59, s94, 0x60000
	v_or_b32_e32 v12, 16, v154
	v_mov_b32_e32 v13, v155
	v_or_b32_e32 v20, 32, v154
	v_mov_b32_e32 v21, v155
	v_or_b32_e32 v154, 48, v154
	s_add_u32 s6, s67, s59
	v_lshlrev_b64 v[120:121], 11, v[12:13]
	v_lshlrev_b64 v[118:119], 11, v[20:21]
	v_lshlrev_b64 v[116:117], 11, v[154:155]
	s_addc_u32 s7, s4, s95
	v_lshl_add_u64 v[16:17], v[28:29], 0, v[120:121]
	v_lshl_add_u64 v[24:25], v[28:29], 0, v[118:119]
	v_lshl_add_u64 v[32:33], v[28:29], 0, v[116:117]
	s_add_u32 s94, s5, s59
	global_load_dwordx4 v[12:15], v[16:17], off
	s_nop 0
	global_load_dwordx4 v[16:19], v[16:17], off offset:64
	s_nop 0
	global_load_dwordx4 v[20:23], v[24:25], off
	s_nop 0
	global_load_dwordx4 v[24:27], v[24:25], off offset:64
	s_nop 0
	global_load_dwordx4 v[28:31], v[32:33], off
	s_nop 0
	global_load_dwordx4 v[32:35], v[32:33], off offset:64
	s_waitcnt vmcnt(0)
	s_waitcnt lgkmcnt(0)
	s_barrier
	s_addc_u32 s95, s58, s95
	s_add_i32 s59, s69, 0x18000
	s_mov_b32 s76, m0
	s_mov_b32 m0, s59
	s_nop 0
	global_load_lds_dwordx4 v221, s[6:7]
	s_mov_b32 m0, s76
	s_add_i32 s66, s69, 0x1c000
	s_mov_b32 s59, m0
	s_mov_b32 m0, s66
	s_nop 0
	global_load_lds_dwordx4 v222, s[94:95]
	s_mov_b32 m0, s59
	s_add_i32 s59, s69, 0x1a000
	s_mov_b32 s66, m0
	s_mov_b32 m0, s59
	s_nop 0
	global_load_lds_dwordx4 v223, s[6:7]
	s_mov_b32 m0, s66
	s_add_i32 s6, s69, 0x1e000
	s_mov_b32 s7, m0
	s_mov_b32 m0, s6
	s_nop 0
	global_load_lds_dwordx4 v224, s[94:95]
	s_mov_b32 m0, s7
	v_mov_b32_e32 v48, 0
	v_mov_b32_e32 v49, 0
	v_mov_b32_e32 v50, 0
	v_mov_b32_e32 v51, 0
	v_mov_b32_e32 v44, 0
	v_mov_b32_e32 v45, 0
	v_mov_b32_e32 v46, 0
	v_mov_b32_e32 v47, 0
	v_mov_b32_e32 v40, 0
	v_mov_b32_e32 v41, 0
	v_mov_b32_e32 v42, 0
	v_mov_b32_e32 v43, 0
	v_mov_b32_e32 v36, 0
	v_mov_b32_e32 v37, 0
	v_mov_b32_e32 v38, 0
	v_mov_b32_e32 v39, 0
	v_mov_b32_e32 v126, 0
	v_mov_b32_e32 v64, 0
	v_mov_b32_e32 v65, 0
	v_mov_b32_e32 v66, 0
	v_mov_b32_e32 v67, 0
	v_mov_b32_e32 v60, 0
	v_mov_b32_e32 v61, 0
	v_mov_b32_e32 v62, 0
	v_mov_b32_e32 v63, 0
	v_mov_b32_e32 v56, 0
	v_mov_b32_e32 v57, 0
	v_mov_b32_e32 v58, 0
	v_mov_b32_e32 v59, 0
	v_mov_b32_e32 v52, 0
	v_mov_b32_e32 v53, 0
	v_mov_b32_e32 v54, 0
	v_mov_b32_e32 v55, 0
	v_mov_b32_e32 v127, 0
	v_mov_b32_e32 v80, 0
	v_mov_b32_e32 v81, 0
	v_mov_b32_e32 v82, 0
	v_mov_b32_e32 v83, 0
	v_mov_b32_e32 v76, 0
	v_mov_b32_e32 v77, 0
	v_mov_b32_e32 v78, 0
	v_mov_b32_e32 v79, 0
	v_mov_b32_e32 v72, 0
	v_mov_b32_e32 v73, 0
	v_mov_b32_e32 v74, 0
	v_mov_b32_e32 v75, 0
	v_mov_b32_e32 v68, 0
	v_mov_b32_e32 v69, 0
	v_mov_b32_e32 v70, 0
	v_mov_b32_e32 v71, 0
	v_mov_b32_e32 v124, 0
	v_mov_b32_e32 v84, 0
	v_mov_b32_e32 v85, 0
	v_mov_b32_e32 v86, 0
	v_mov_b32_e32 v87, 0
	v_mov_b32_e32 v92, 0
	v_mov_b32_e32 v93, 0
	v_mov_b32_e32 v94, 0
	v_mov_b32_e32 v95, 0
	v_mov_b32_e32 v88, 0
	v_mov_b32_e32 v89, 0
	v_mov_b32_e32 v90, 0
	v_mov_b32_e32 v91, 0
	v_mov_b32_e32 v96, 0
	v_mov_b32_e32 v97, 0
	v_mov_b32_e32 v98, 0
	v_mov_b32_e32 v99, 0
	v_mov_b32_e32 v125, 0
	s_mov_b32 s96, 4
	s_lshl_b32 s6, s60, 6
	s_addk_i32 s6, 0xff00
	s_add_u32 s94, s61, s6
	s_addc_u32 s95, 0, 0
	s_mov_b32 vcc_lo, 0
	s_add_i32 s76, s65, 0
	v_add_u32_e32 v144, s76, v111
	v_add3_u32 v193, s76, v210, v205
	v_add_u32_e32 v145, v144, v204
	v_add_u32_e32 v144, v144, v203
	ds_read_b128 v[160:163], v144
	ds_read_b128 v[164:167], v145
	ds_read_b128 v[168:171], v144 offset:2048
	ds_read_b128 v[172:175], v145 offset:2048
	ds_read_b128 v[128:131], v144 offset:4096
	ds_read_b128 v[132:135], v145 offset:4096
	ds_read_b128 v[136:139], v144 offset:6144
	ds_read_b128 v[140:143], v145 offset:6144
	v_add_u32_e32 v158, v193, v206
	v_add_u32_e32 v159, v193, v207
	v_add_u32_e32 v192, v193, v208
	v_add_u32_e32 v193, v193, v209
	s_waitcnt lgkmcnt(4)
	v_mfma_f32_16x16x32_bf16 v[228:231], v[160:163], v[4:7], v[0:3]
	v_mfma_f32_16x16x32_bf16 v[232:235], v[168:171], v[4:7], v[0:3]
	v_mfma_f32_16x16x32_bf16 v[228:231], v[164:167], v[8:11], v[228:231]
	v_mfma_f32_16x16x32_bf16 v[232:235], v[172:175], v[8:11], v[232:235]
	ds_read_b64_tr_b16 v[176:177], v158 offset:16384
	ds_read_b64_tr_b16 v[178:179], v158 offset:18432
	ds_read_b64_tr_b16 v[180:181], v159 offset:16384
	ds_read_b64_tr_b16 v[182:183], v159 offset:18432
	ds_read_b64_tr_b16 v[184:185], v192 offset:16384
	ds_read_b64_tr_b16 v[186:187], v192 offset:18432
	ds_read_b64_tr_b16 v[188:189], v193 offset:16384
	ds_read_b64_tr_b16 v[190:191], v193 offset:18432
	v_mfma_f32_16x16x32_bf16 v[236:239], v[160:163], v[12:15], v[0:3]
	v_exp_f32_e32 v228, v228
	v_exp_f32_e32 v229, v229
	v_exp_f32_e32 v230, v230
	v_add_f32_e32 v154, v228, v229
	v_mfma_f32_16x16x32_bf16 v[104:107], v[168:171], v[12:15], v[0:3]
	v_exp_f32_e32 v231, v231
	v_add_f32_e32 v154, v154, v230
	v_exp_f32_e32 v232, v232
	v_add_f32_e32 v154, v154, v231
	v_mfma_f32_16x16x32_bf16 v[236:239], v[164:167], v[16:19], v[236:239]
	v_exp_f32_e32 v233, v233
	v_add_f32_e32 v154, v154, v232
	v_exp_f32_e32 v234, v234
	v_add_f32_e32 v154, v154, v233
	v_cvt_pk_bf16_f32 v228, v228, v229
	v_mfma_f32_16x16x32_bf16 v[104:107], v[172:175], v[16:19], v[104:107]
	v_exp_f32_e32 v235, v235
	v_add_f32_e32 v154, v154, v234
	v_cvt_pk_bf16_f32 v229, v230, v231
	v_cvt_pk_bf16_f32 v230, v232, v233
	v_cvt_pk_bf16_f32 v231, v234, v235
	v_add_f32_e32 v154, v154, v235
	v_add_f32_e32 v126, v126, v154
	s_waitcnt lgkmcnt(0)
; #define LAS __attribute__((address_space(3)))
; __device__ __forceinline__ s16x4 vtr(const LAS unsigned char* p) { return __builtin_bit_cast(s16x4, __builtin_amdgcn_ds_read_tr16_b64_v4i16((LAS v4i16_t*)p)); }
; __device__ __forceinline__ bf16x8 cat8(s16x4 a, s16x4 b) { return (bf16x8){a[0], a[1], a[2], a[3], b[0], b[1], b[2], b[3]}; }
; __device__ __forceinline__ bf16x8 pack8(const f32x4& a, const f32x4& b) { u32x4 w; w.x = pkbf(a[0], a[1]); w.y = pkbf(a[2], a[3]); w.z = pkbf(b[0], b[1]); w.w = pkbf(b[2], b[3]); return __builtin_bit_cast(bf16x8, w); }
;     ...
;     for (int gh = 0; gh < 4 / GPB; ++gh) {
;         f32x4 S[GPB][4];
; #pragma unroll
;         for (int kb = 0; kb < 4; ++kb) {
;             const bf16x8 kf0 = *(const LAS bf16x8*)(kb0 + (16 * kb) * 128 + kx0), kf1 = *(const LAS bf16x8*)(kb0 + (16 * kb) * 128 + kx1);
; #pragma unroll
;             for (int gi = 0; gi < GPB; ++gi) { S[gi][kb] = __builtin_amdgcn_mfma_f32_16x16x32_bf16(kf0, qf[GPB * gh + gi][0], cinit, 0, 0, 0);
;                 S[gi][kb] = __builtin_amdgcn_mfma_f32_16x16x32_bf16(kf1, qf[GPB * gh + gi][1], S[gi][kb], 0, 0, 0); } }
;         bf16x8 pf[GPB][2];
; #pragma unroll
;         for (int gi = 0; gi < GPB; ++gi) {
;             if (MASK) {
; #pragma unroll
;                 for (int kb = 0; kb < 4; ++kb)
; #pragma unroll
;                     for (int i = 0; i < 4; ++i) { const int rel = rel0 + 16 * kb + 4 * g + i; S[gi][kb][i] = ((unsigned)(rel + 128) > 256u) ? NEGBIG : S[gi][kb][i]; }
;             }
;             ls[GPB * gh + gi] += exp_step<4>(S[gi]);
;             pf[gi][0] = pack8(S[gi][0], S[gi][1]); pf[gi][1] = pack8(S[gi][2], S[gi][3]);
;         }
; #pragma unroll
;         for (int kc = 0; kc < 2; ++kc)
; #pragma unroll
;             for (int db = 0; db < 4; ++db) {
;                 const LAS unsigned char* va = vrow + ((db ^ swz) << 5) + (32 * kc) * 128;
;                 const bf16x8 vf = cat8(vtr(va), vtr(va + 16 * 128));
; #pragma unroll
;                 for (int gi = 0; gi < GPB; ++gi) O[GPB * gh + gi][db] = __builtin_amdgcn_mfma_f32_16x16x32_bf16(vf, pf[gi][kc], O[GPB * gh + gi][db], 0, 0, 0);
;             }
	v_mfma_f32_16x16x32_bf16 v[244:247], v[160:163], v[20:23], v[0:3]
	v_exp_f32_e32 v236, v236
	v_exp_f32_e32 v237, v237
	v_mfma_f32_16x16x32_bf16 v[248:251], v[168:171], v[20:23], v[0:3]
	v_exp_f32_e32 v238, v238
	v_add_f32_e32 v154, v236, v237
	v_mfma_f32_16x16x32_bf16 v[244:247], v[164:167], v[24:27], v[244:247]
	v_exp_f32_e32 v239, v239
	v_add_f32_e32 v154, v154, v238
	v_mfma_f32_16x16x32_bf16 v[248:251], v[172:175], v[24:27], v[248:251]
	v_exp_f32_e32 v104, v104
	v_add_f32_e32 v154, v154, v239
	v_mfma_f32_16x16x32_bf16 v[48:51], v[176:179], v[228:231], v[48:51]
	v_exp_f32_e32 v105, v105
	v_add_f32_e32 v154, v154, v104
	v_mfma_f32_16x16x32_bf16 v[44:47], v[180:183], v[228:231], v[44:47]
	v_exp_f32_e32 v106, v106
	v_add_f32_e32 v154, v154, v105
	v_cvt_pk_bf16_f32 v236, v236, v237
	v_mfma_f32_16x16x32_bf16 v[40:43], v[184:187], v[228:231], v[40:43]
	v_exp_f32_e32 v107, v107
	v_add_f32_e32 v154, v154, v106
	v_cvt_pk_bf16_f32 v237, v238, v239
	v_mfma_f32_16x16x32_bf16 v[36:39], v[188:191], v[228:231], v[36:39]
	v_cvt_pk_bf16_f32 v238, v104, v105
	v_cvt_pk_bf16_f32 v239, v106, v107
	v_add_f32_e32 v154, v154, v107
	v_add_f32_e32 v127, v127, v154
	v_mfma_f32_16x16x32_bf16 v[228:231], v[160:163], v[28:31], v[0:3]
	v_exp_f32_e32 v244, v244
	v_exp_f32_e32 v245, v245
	v_mfma_f32_16x16x32_bf16 v[232:235], v[168:171], v[28:31], v[0:3]
	v_exp_f32_e32 v246, v246
	v_add_f32_e32 v154, v244, v245
	v_mfma_f32_16x16x32_bf16 v[228:231], v[164:167], v[32:35], v[228:231]
	v_exp_f32_e32 v247, v247
	v_add_f32_e32 v154, v154, v246
	v_mfma_f32_16x16x32_bf16 v[232:235], v[172:175], v[32:35], v[232:235]
	v_exp_f32_e32 v248, v248
	v_add_f32_e32 v154, v154, v247
	v_mfma_f32_16x16x32_bf16 v[64:67], v[176:179], v[236:239], v[64:67]
	v_exp_f32_e32 v249, v249
	v_add_f32_e32 v154, v154, v248
	v_mfma_f32_16x16x32_bf16 v[60:63], v[180:183], v[236:239], v[60:63]
	v_exp_f32_e32 v250, v250
	v_add_f32_e32 v154, v154, v249
	v_cvt_pk_bf16_f32 v244, v244, v245
	v_mfma_f32_16x16x32_bf16 v[56:59], v[184:187], v[236:239], v[56:59]
	v_exp_f32_e32 v251, v251
	v_add_f32_e32 v154, v154, v250
	v_cvt_pk_bf16_f32 v245, v246, v247
	v_mfma_f32_16x16x32_bf16 v[52:55], v[188:191], v[236:239], v[52:55]
	v_cvt_pk_bf16_f32 v246, v248, v249
	v_cvt_pk_bf16_f32 v247, v250, v251
	v_add_f32_e32 v154, v154, v251
	v_add_f32_e32 v124, v124, v154
	ds_read_b64_tr_b16 v[160:161], v158 offset:20480
	ds_read_b64_tr_b16 v[162:163], v158 offset:22528
	ds_read_b64_tr_b16 v[164:165], v159 offset:20480
	ds_read_b64_tr_b16 v[166:167], v159 offset:22528
	ds_read_b64_tr_b16 v[168:169], v192 offset:20480
	ds_read_b64_tr_b16 v[170:171], v192 offset:22528
	ds_read_b64_tr_b16 v[172:173], v193 offset:20480
	ds_read_b64_tr_b16 v[174:175], v193 offset:22528
	v_mfma_f32_16x16x32_bf16 v[236:239], v[128:131], v[4:7], v[0:3]
	v_exp_f32_e32 v228, v228
	v_exp_f32_e32 v229, v229
	v_mfma_f32_16x16x32_bf16 v[104:107], v[136:139], v[4:7], v[0:3]
	v_exp_f32_e32 v230, v230
	v_add_f32_e32 v154, v228, v229
	v_mfma_f32_16x16x32_bf16 v[236:239], v[132:135], v[8:11], v[236:239]
	v_exp_f32_e32 v231, v231
	v_add_f32_e32 v154, v154, v230
	v_mfma_f32_16x16x32_bf16 v[104:107], v[140:143], v[8:11], v[104:107]
	v_exp_f32_e32 v232, v232
	v_add_f32_e32 v154, v154, v231
	v_mfma_f32_16x16x32_bf16 v[80:83], v[176:179], v[244:247], v[80:83]
	v_exp_f32_e32 v233, v233
	v_add_f32_e32 v154, v154, v232
	v_mfma_f32_16x16x32_bf16 v[76:79], v[180:183], v[244:247], v[76:79]
	v_exp_f32_e32 v234, v234
	v_add_f32_e32 v154, v154, v233
	v_cvt_pk_bf16_f32 v228, v228, v229
	v_mfma_f32_16x16x32_bf16 v[72:75], v[184:187], v[244:247], v[72:75]
	v_exp_f32_e32 v235, v235
	v_add_f32_e32 v154, v154, v234
	v_cvt_pk_bf16_f32 v229, v230, v231
	v_mfma_f32_16x16x32_bf16 v[68:71], v[188:191], v[244:247], v[68:71]
	v_cvt_pk_bf16_f32 v230, v232, v233
	v_cvt_pk_bf16_f32 v231, v234, v235
	v_add_f32_e32 v154, v154, v235
	v_add_f32_e32 v125, v125, v154
	v_mfma_f32_16x16x32_bf16 v[244:247], v[128:131], v[12:15], v[0:3]
	v_exp_f32_e32 v236, v236
	v_exp_f32_e32 v237, v237
	v_mfma_f32_16x16x32_bf16 v[248:251], v[136:139], v[12:15], v[0:3]
	v_exp_f32_e32 v238, v238
	v_add_f32_e32 v154, v236, v237
	v_mfma_f32_16x16x32_bf16 v[244:247], v[132:135], v[16:19], v[244:247]
	v_exp_f32_e32 v239, v239
	v_add_f32_e32 v154, v154, v238
	v_mfma_f32_16x16x32_bf16 v[248:251], v[140:143], v[16:19], v[248:251]
	v_exp_f32_e32 v104, v104
	v_add_f32_e32 v154, v154, v239
	v_mfma_f32_16x16x32_bf16 v[84:87], v[176:179], v[228:231], v[84:87]
	v_exp_f32_e32 v105, v105
	v_add_f32_e32 v154, v154, v104
	v_mfma_f32_16x16x32_bf16 v[92:95], v[180:183], v[228:231], v[92:95]
	v_exp_f32_e32 v106, v106
	v_add_f32_e32 v154, v154, v105
	v_cvt_pk_bf16_f32 v236, v236, v237
	v_mfma_f32_16x16x32_bf16 v[88:91], v[184:187], v[228:231], v[88:91]
	v_exp_f32_e32 v107, v107
	v_add_f32_e32 v154, v154, v106
	v_cvt_pk_bf16_f32 v237, v238, v239
	v_mfma_f32_16x16x32_bf16 v[96:99], v[188:191], v[228:231], v[96:99]
	v_cvt_pk_bf16_f32 v238, v104, v105
	v_cvt_pk_bf16_f32 v239, v106, v107
	v_add_f32_e32 v154, v154, v107
	v_add_f32_e32 v126, v126, v154
	s_waitcnt lgkmcnt(0)
; #define LAS __attribute__((address_space(3)))
; __device__ __forceinline__ s16x4 vtr(const LAS unsigned char* p) { return __builtin_bit_cast(s16x4, __builtin_amdgcn_ds_read_tr16_b64_v4i16((LAS v4i16_t*)p)); }
; __device__ __forceinline__ bf16x8 cat8(s16x4 a, s16x4 b) { return (bf16x8){a[0], a[1], a[2], a[3], b[0], b[1], b[2], b[3]}; }
;     ...
;         for (int kb = 0; kb < 4; ++kb) {
;             const bf16x8 kf0 = *(const LAS bf16x8*)(kb0 + (16 * kb) * 128 + kx0), kf1 = *(const LAS bf16x8*)(kb0 + (16 * kb) * 128 + kx1);
; #pragma unroll
;             for (int gi = 0; gi < GPB; ++gi) { S[gi][kb] = __builtin_amdgcn_mfma_f32_16x16x32_bf16(kf0, qf[GPB * gh + gi][0], cinit, 0, 0, 0);
;                 S[gi][kb] = __builtin_amdgcn_mfma_f32_16x16x32_bf16(kf1, qf[GPB * gh + gi][1], S[gi][kb], 0, 0, 0); } }
;         bf16x8 pf[GPB][2];
; #pragma unroll
;         for (int gi = 0; gi < GPB; ++gi) {
;             if (MASK) {
; #pragma unroll
;                 for (int kb = 0; kb < 4; ++kb)
; #pragma unroll
;                     for (int i = 0; i < 4; ++i) { const int rel = rel0 + 16 * kb + 4 * g + i; S[gi][kb][i] = ((unsigned)(rel + 128) > 256u) ? NEGBIG : S[gi][kb][i]; }
;             }
;             ls[GPB * gh + gi] += exp_step<4>(S[gi]);
;             pf[gi][0] = pack8(S[gi][0], S[gi][1]); pf[gi][1] = pack8(S[gi][2], S[gi][3]);
;         }
; #pragma unroll
;         for (int kc = 0; kc < 2; ++kc)
; #pragma unroll
;             for (int db = 0; db < 4; ++db) {
;                 const LAS unsigned char* va = vrow + ((db ^ swz) << 5) + (32 * kc) * 128;
;                 const bf16x8 vf = cat8(vtr(va), vtr(va + 16 * 128));
; #pragma unroll
;                 for (int gi = 0; gi < GPB; ++gi) O[GPB * gh + gi][db] = __builtin_amdgcn_mfma_f32_16x16x32_bf16(vf, pf[gi][kc], O[GPB * gh + gi][db], 0, 0, 0);
;             }
; __device__ __forceinline__ void na_phase(LAS unsigned char* lds, const bf16_t* Q, const bf16_t* K, const bf16_t* V, bf16_t* Ob, const float* rpb, float negb) {
;     ...
;         for (int t = 0; t < 4; ++t) {
;             dma_tile<2>(lds + ((t + 3) & 3) * NA_BUF, K, V, NA_ROW0(t + 3), DM, dl, w);
;             const LAS unsigned char* buf = lds + (t & 3) * NA_BUF;
;             full_tile<0, 1, 2>(O, ls, qf, negb, buf + hh * 8192, buf + 2 * 8192 + hh * 8192, lane, 0);
;             ring_wait<4>();
	v_mfma_f32_16x16x32_bf16 v[228:231], v[128:131], v[20:23], v[0:3]
	v_exp_f32_e32 v244, v244
	v_exp_f32_e32 v245, v245
	v_mfma_f32_16x16x32_bf16 v[232:235], v[136:139], v[20:23], v[0:3]
	v_exp_f32_e32 v246, v246
	v_add_f32_e32 v154, v244, v245
	v_mfma_f32_16x16x32_bf16 v[228:231], v[132:135], v[24:27], v[228:231]
	v_exp_f32_e32 v247, v247
	v_add_f32_e32 v154, v154, v246
	v_mfma_f32_16x16x32_bf16 v[232:235], v[140:143], v[24:27], v[232:235]
	v_exp_f32_e32 v248, v248
	v_add_f32_e32 v154, v154, v247
	v_mfma_f32_16x16x32_bf16 v[48:51], v[160:163], v[236:239], v[48:51]
	v_exp_f32_e32 v249, v249
	v_add_f32_e32 v154, v154, v248
	v_mfma_f32_16x16x32_bf16 v[44:47], v[164:167], v[236:239], v[44:47]
	v_exp_f32_e32 v250, v250
	v_add_f32_e32 v154, v154, v249
	v_cvt_pk_bf16_f32 v244, v244, v245
	v_mfma_f32_16x16x32_bf16 v[40:43], v[168:171], v[236:239], v[40:43]
	v_exp_f32_e32 v251, v251
	v_add_f32_e32 v154, v154, v250
	v_cvt_pk_bf16_f32 v245, v246, v247
	v_mfma_f32_16x16x32_bf16 v[36:39], v[172:175], v[236:239], v[36:39]
	v_cvt_pk_bf16_f32 v246, v248, v249
	v_cvt_pk_bf16_f32 v247, v250, v251
	v_add_f32_e32 v154, v154, v251
	v_add_f32_e32 v127, v127, v154
	v_mfma_f32_16x16x32_bf16 v[236:239], v[128:131], v[28:31], v[0:3]
	v_exp_f32_e32 v228, v228
	v_exp_f32_e32 v229, v229
	v_mfma_f32_16x16x32_bf16 v[104:107], v[136:139], v[28:31], v[0:3]
	v_exp_f32_e32 v230, v230
	v_add_f32_e32 v154, v228, v229
	v_mfma_f32_16x16x32_bf16 v[236:239], v[132:135], v[32:35], v[236:239]
	v_exp_f32_e32 v231, v231
	v_add_f32_e32 v154, v154, v230
	v_mfma_f32_16x16x32_bf16 v[104:107], v[140:143], v[32:35], v[104:107]
	v_exp_f32_e32 v232, v232
	v_add_f32_e32 v154, v154, v231
	v_mfma_f32_16x16x32_bf16 v[64:67], v[160:163], v[244:247], v[64:67]
	v_exp_f32_e32 v233, v233
	v_add_f32_e32 v154, v154, v232
	v_mfma_f32_16x16x32_bf16 v[60:63], v[164:167], v[244:247], v[60:63]
	v_exp_f32_e32 v234, v234
	v_add_f32_e32 v154, v154, v233
	v_cvt_pk_bf16_f32 v228, v228, v229
	v_mfma_f32_16x16x32_bf16 v[56:59], v[168:171], v[244:247], v[56:59]
	v_exp_f32_e32 v235, v235
	v_add_f32_e32 v154, v154, v234
	v_cvt_pk_bf16_f32 v229, v230, v231
	v_mfma_f32_16x16x32_bf16 v[52:55], v[172:175], v[244:247], v[52:55]
	v_cvt_pk_bf16_f32 v230, v232, v233
	v_cvt_pk_bf16_f32 v231, v234, v235
	v_add_f32_e32 v154, v154, v235
	v_add_f32_e32 v124, v124, v154
	v_mfma_f32_16x16x32_bf16 v[80:83], v[160:163], v[228:231], v[80:83]
	v_exp_f32_e32 v236, v236
	v_exp_f32_e32 v237, v237
	v_exp_f32_e32 v238, v238
	v_add_f32_e32 v154, v236, v237
	v_mfma_f32_16x16x32_bf16 v[76:79], v[164:167], v[228:231], v[76:79]
	v_exp_f32_e32 v239, v239
	v_add_f32_e32 v154, v154, v238
	v_exp_f32_e32 v104, v104
	v_add_f32_e32 v154, v154, v239
	v_mfma_f32_16x16x32_bf16 v[72:75], v[168:171], v[228:231], v[72:75]
	v_exp_f32_e32 v105, v105
	v_add_f32_e32 v154, v154, v104
	v_exp_f32_e32 v106, v106
	v_add_f32_e32 v154, v154, v105
	v_cvt_pk_bf16_f32 v236, v236, v237
	v_mfma_f32_16x16x32_bf16 v[68:71], v[172:175], v[228:231], v[68:71]
	v_exp_f32_e32 v107, v107
	v_add_f32_e32 v154, v154, v106
	v_cvt_pk_bf16_f32 v237, v238, v239
	v_cvt_pk_bf16_f32 v238, v104, v105
	v_cvt_pk_bf16_f32 v239, v106, v107
	v_add_f32_e32 v154, v154, v107
	v_add_f32_e32 v125, v125, v154
	v_mfma_f32_16x16x32_bf16 v[84:87], v[160:163], v[236:239], v[84:87]
	v_mfma_f32_16x16x32_bf16 v[92:95], v[164:167], v[236:239], v[92:95]
	v_mfma_f32_16x16x32_bf16 v[88:91], v[168:171], v[236:239], v[88:91]
	v_mfma_f32_16x16x32_bf16 v[96:99], v[172:175], v[236:239], v[96:99]
	s_waitcnt vmcnt(8)
	s_barrier
	s_cmp_lt_i32 s96, s93
	s_cselect_b32 s7, s95, 0
	s_cselect_b32 s6, s94, s82
	s_lshl_b64 s[6:7], s[6:7], 11
	s_add_u32 s76, s67, s6
	s_addc_u32 s77, s4, s7
	s_add_u32 s6, s5, s6
	s_addc_u32 s7, s58, s7
	s_add_i32 s59, s69, vcc_lo
	s_mov_b32 vcc_hi, m0
	s_mov_b32 m0, s59
	s_nop 0
	global_load_lds_dwordx4 v221, s[76:77]
	s_mov_b32 m0, vcc_hi
	s_add_i32 s66, s59, 0x4000
	s_mov_b32 vcc_hi, m0
	s_mov_b32 m0, s66
	s_nop 0
	global_load_lds_dwordx4 v222, s[6:7]
	s_mov_b32 m0, vcc_hi
	s_add_i32 s66, s59, 0x2000
	s_mov_b32 vcc_hi, m0
	s_mov_b32 m0, s66
	s_nop 0
	global_load_lds_dwordx4 v223, s[76:77]
	s_mov_b32 m0, vcc_hi
	s_addk_i32 s59, 0x6000
	s_mov_b32 s66, m0
	s_mov_b32 m0, s59
	s_nop 0
	global_load_lds_dwordx4 v224, s[6:7]
	s_mov_b32 m0, s66
	s_add_i32 s76, s65, vcc_lo
	s_add_i32 s76, s76, 0x8000
	v_add_u32_e32 v144, s76, v111
	v_add3_u32 v193, s76, v210, v205
	v_add_u32_e32 v145, v144, v204
	v_add_u32_e32 v144, v144, v203
	ds_read_b128 v[160:163], v144
	ds_read_b128 v[164:167], v145
	ds_read_b128 v[168:171], v144 offset:2048
	ds_read_b128 v[172:175], v145 offset:2048
	ds_read_b128 v[128:131], v144 offset:4096
	ds_read_b128 v[132:135], v145 offset:4096
	ds_read_b128 v[136:139], v144 offset:6144
	ds_read_b128 v[140:143], v145 offset:6144
	v_add_u32_e32 v158, v193, v206
	v_add_u32_e32 v159, v193, v207
	v_add_u32_e32 v192, v193, v208
	v_add_u32_e32 v193, v193, v209
	s_waitcnt lgkmcnt(4)
; #define LAS __attribute__((address_space(3)))
; __device__ __forceinline__ s16x4 vtr(const LAS unsigned char* p) { return __builtin_bit_cast(s16x4, __builtin_amdgcn_ds_read_tr16_b64_v4i16((LAS v4i16_t*)p)); }
; __device__ __forceinline__ bf16x8 cat8(s16x4 a, s16x4 b) { return (bf16x8){a[0], a[1], a[2], a[3], b[0], b[1], b[2], b[3]}; }
; __device__ __forceinline__ bf16x8 pack8(const f32x4& a, const f32x4& b) { u32x4 w; w.x = pkbf(a[0], a[1]); w.y = pkbf(a[2], a[3]); w.z = pkbf(b[0], b[1]); w.w = pkbf(b[2], b[3]); return __builtin_bit_cast(bf16x8, w); }
;     ...
;     for (int gh = 0; gh < 4 / GPB; ++gh) {
;         f32x4 S[GPB][4];
; #pragma unroll
;         for (int kb = 0; kb < 4; ++kb) {
;             const bf16x8 kf0 = *(const LAS bf16x8*)(kb0 + (16 * kb) * 128 + kx0), kf1 = *(const LAS bf16x8*)(kb0 + (16 * kb) * 128 + kx1);
; #pragma unroll
;             for (int gi = 0; gi < GPB; ++gi) { S[gi][kb] = __builtin_amdgcn_mfma_f32_16x16x32_bf16(kf0, qf[GPB * gh + gi][0], cinit, 0, 0, 0);
;                 S[gi][kb] = __builtin_amdgcn_mfma_f32_16x16x32_bf16(kf1, qf[GPB * gh + gi][1], S[gi][kb], 0, 0, 0); } }
;         bf16x8 pf[GPB][2];
; #pragma unroll
;         for (int gi = 0; gi < GPB; ++gi) {
;             if (MASK) {
; #pragma unroll
;                 for (int kb = 0; kb < 4; ++kb)
; #pragma unroll
;                     for (int i = 0; i < 4; ++i) { const int rel = rel0 + 16 * kb + 4 * g + i; S[gi][kb][i] = ((unsigned)(rel + 128) > 256u) ? NEGBIG : S[gi][kb][i]; }
;             }
;             ls[GPB * gh + gi] += exp_step<4>(S[gi]);
;             pf[gi][0] = pack8(S[gi][0], S[gi][1]); pf[gi][1] = pack8(S[gi][2], S[gi][3]);
;         }
; #pragma unroll
;         for (int kc = 0; kc < 2; ++kc)
; #pragma unroll
;             for (int db = 0; db < 4; ++db) {
;                 const LAS unsigned char* va = vrow + ((db ^ swz) << 5) + (32 * kc) * 128;
;                 const bf16x8 vf = cat8(vtr(va), vtr(va + 16 * 128));
; #pragma unroll
;                 for (int gi = 0; gi < GPB; ++gi) O[GPB * gh + gi][db] = __builtin_amdgcn_mfma_f32_16x16x32_bf16(vf, pf[gi][kc], O[GPB * gh + gi][db], 0, 0, 0);
;             }
	v_mfma_f32_16x16x32_bf16 v[228:231], v[160:163], v[4:7], v[0:3]
	v_mfma_f32_16x16x32_bf16 v[232:235], v[168:171], v[4:7], v[0:3]
	v_mfma_f32_16x16x32_bf16 v[228:231], v[164:167], v[8:11], v[228:231]
	v_mfma_f32_16x16x32_bf16 v[232:235], v[172:175], v[8:11], v[232:235]
	ds_read_b64_tr_b16 v[176:177], v158 offset:16384
	ds_read_b64_tr_b16 v[178:179], v158 offset:18432
	ds_read_b64_tr_b16 v[180:181], v159 offset:16384
	ds_read_b64_tr_b16 v[182:183], v159 offset:18432
	ds_read_b64_tr_b16 v[184:185], v192 offset:16384
	ds_read_b64_tr_b16 v[186:187], v192 offset:18432
	ds_read_b64_tr_b16 v[188:189], v193 offset:16384
	ds_read_b64_tr_b16 v[190:191], v193 offset:18432
	v_mfma_f32_16x16x32_bf16 v[236:239], v[160:163], v[12:15], v[0:3]
	v_exp_f32_e32 v228, v228
	v_exp_f32_e32 v229, v229
	v_exp_f32_e32 v230, v230
	v_add_f32_e32 v154, v228, v229
	v_mfma_f32_16x16x32_bf16 v[104:107], v[168:171], v[12:15], v[0:3]
	v_exp_f32_e32 v231, v231
	v_add_f32_e32 v154, v154, v230
	v_exp_f32_e32 v232, v232
	v_add_f32_e32 v154, v154, v231
	v_mfma_f32_16x16x32_bf16 v[236:239], v[164:167], v[16:19], v[236:239]
	v_exp_f32_e32 v233, v233
	v_add_f32_e32 v154, v154, v232
	v_exp_f32_e32 v234, v234
	v_add_f32_e32 v154, v154, v233
	v_cvt_pk_bf16_f32 v228, v228, v229
	v_mfma_f32_16x16x32_bf16 v[104:107], v[172:175], v[16:19], v[104:107]
	v_exp_f32_e32 v235, v235
	v_add_f32_e32 v154, v154, v234
	v_cvt_pk_bf16_f32 v229, v230, v231
	v_cvt_pk_bf16_f32 v230, v232, v233
	v_cvt_pk_bf16_f32 v231, v234, v235
	v_add_f32_e32 v154, v154, v235
	v_add_f32_e32 v126, v126, v154
	s_waitcnt lgkmcnt(0)
	v_mfma_f32_16x16x32_bf16 v[244:247], v[160:163], v[20:23], v[0:3]
	v_exp_f32_e32 v236, v236
	v_exp_f32_e32 v237, v237
	v_mfma_f32_16x16x32_bf16 v[248:251], v[168:171], v[20:23], v[0:3]
	v_exp_f32_e32 v238, v238
	v_add_f32_e32 v154, v236, v237
	v_mfma_f32_16x16x32_bf16 v[244:247], v[164:167], v[24:27], v[244:247]
	v_exp_f32_e32 v239, v239
	v_add_f32_e32 v154, v154, v238
	v_mfma_f32_16x16x32_bf16 v[248:251], v[172:175], v[24:27], v[248:251]
	v_exp_f32_e32 v104, v104
	v_add_f32_e32 v154, v154, v239
	v_mfma_f32_16x16x32_bf16 v[48:51], v[176:179], v[228:231], v[48:51]
	v_exp_f32_e32 v105, v105
	v_add_f32_e32 v154, v154, v104
	v_mfma_f32_16x16x32_bf16 v[44:47], v[180:183], v[228:231], v[44:47]
	v_exp_f32_e32 v106, v106
	v_add_f32_e32 v154, v154, v105
	v_cvt_pk_bf16_f32 v236, v236, v237
	v_mfma_f32_16x16x32_bf16 v[40:43], v[184:187], v[228:231], v[40:43]
	v_exp_f32_e32 v107, v107
	v_add_f32_e32 v154, v154, v106
	v_cvt_pk_bf16_f32 v237, v238, v239
	v_mfma_f32_16x16x32_bf16 v[36:39], v[188:191], v[228:231], v[36:39]
	v_cvt_pk_bf16_f32 v238, v104, v105
	v_cvt_pk_bf16_f32 v239, v106, v107
	v_add_f32_e32 v154, v154, v107
	v_add_f32_e32 v127, v127, v154
	v_mfma_f32_16x16x32_bf16 v[228:231], v[160:163], v[28:31], v[0:3]
	v_exp_f32_e32 v244, v244
	v_exp_f32_e32 v245, v245
	v_mfma_f32_16x16x32_bf16 v[232:235], v[168:171], v[28:31], v[0:3]
	v_exp_f32_e32 v246, v246
	v_add_f32_e32 v154, v244, v245
	v_mfma_f32_16x16x32_bf16 v[228:231], v[164:167], v[32:35], v[228:231]
	v_exp_f32_e32 v247, v247
	v_add_f32_e32 v154, v154, v246
	v_mfma_f32_16x16x32_bf16 v[232:235], v[172:175], v[32:35], v[232:235]
	v_exp_f32_e32 v248, v248
	v_add_f32_e32 v154, v154, v247
	v_mfma_f32_16x16x32_bf16 v[64:67], v[176:179], v[236:239], v[64:67]
	v_exp_f32_e32 v249, v249
	v_add_f32_e32 v154, v154, v248
	v_mfma_f32_16x16x32_bf16 v[60:63], v[180:183], v[236:239], v[60:63]
	v_exp_f32_e32 v250, v250
	v_add_f32_e32 v154, v154, v249
	v_cvt_pk_bf16_f32 v244, v244, v245
	v_mfma_f32_16x16x32_bf16 v[56:59], v[184:187], v[236:239], v[56:59]
	v_exp_f32_e32 v251, v251
	v_add_f32_e32 v154, v154, v250
	v_cvt_pk_bf16_f32 v245, v246, v247
	v_mfma_f32_16x16x32_bf16 v[52:55], v[188:191], v[236:239], v[52:55]
	v_cvt_pk_bf16_f32 v246, v248, v249
	v_cvt_pk_bf16_f32 v247, v250, v251
	v_add_f32_e32 v154, v154, v251
	v_add_f32_e32 v124, v124, v154
	ds_read_b64_tr_b16 v[160:161], v158 offset:20480
	ds_read_b64_tr_b16 v[162:163], v158 offset:22528
	ds_read_b64_tr_b16 v[164:165], v159 offset:20480
	ds_read_b64_tr_b16 v[166:167], v159 offset:22528
	ds_read_b64_tr_b16 v[168:169], v192 offset:20480
	ds_read_b64_tr_b16 v[170:171], v192 offset:22528
	ds_read_b64_tr_b16 v[172:173], v193 offset:20480
	ds_read_b64_tr_b16 v[174:175], v193 offset:22528
	v_mfma_f32_16x16x32_bf16 v[236:239], v[128:131], v[4:7], v[0:3]
	v_exp_f32_e32 v228, v228
	v_exp_f32_e32 v229, v229
	v_mfma_f32_16x16x32_bf16 v[104:107], v[136:139], v[4:7], v[0:3]
	v_exp_f32_e32 v230, v230
	v_add_f32_e32 v154, v228, v229
	v_mfma_f32_16x16x32_bf16 v[236:239], v[132:135], v[8:11], v[236:239]
	v_exp_f32_e32 v231, v231
	v_add_f32_e32 v154, v154, v230
	v_mfma_f32_16x16x32_bf16 v[104:107], v[140:143], v[8:11], v[104:107]
	v_exp_f32_e32 v232, v232
	v_add_f32_e32 v154, v154, v231
	v_mfma_f32_16x16x32_bf16 v[80:83], v[176:179], v[244:247], v[80:83]
	v_exp_f32_e32 v233, v233
	v_add_f32_e32 v154, v154, v232
	v_mfma_f32_16x16x32_bf16 v[76:79], v[180:183], v[244:247], v[76:79]
	v_exp_f32_e32 v234, v234
	v_add_f32_e32 v154, v154, v233
	v_cvt_pk_bf16_f32 v228, v228, v229
	v_mfma_f32_16x16x32_bf16 v[72:75], v[184:187], v[244:247], v[72:75]
	v_exp_f32_e32 v235, v235
	v_add_f32_e32 v154, v154, v234
	v_cvt_pk_bf16_f32 v229, v230, v231
	v_mfma_f32_16x16x32_bf16 v[68:71], v[188:191], v[244:247], v[68:71]
	v_cvt_pk_bf16_f32 v230, v232, v233
	v_cvt_pk_bf16_f32 v231, v234, v235
	v_add_f32_e32 v154, v154, v235
	v_add_f32_e32 v125, v125, v154
	v_mfma_f32_16x16x32_bf16 v[244:247], v[128:131], v[12:15], v[0:3]
	v_exp_f32_e32 v236, v236
	v_exp_f32_e32 v237, v237
	v_mfma_f32_16x16x32_bf16 v[248:251], v[136:139], v[12:15], v[0:3]
	v_exp_f32_e32 v238, v238
	v_add_f32_e32 v154, v236, v237
	v_mfma_f32_16x16x32_bf16 v[244:247], v[132:135], v[16:19], v[244:247]
	v_exp_f32_e32 v239, v239
	v_add_f32_e32 v154, v154, v238
	v_mfma_f32_16x16x32_bf16 v[248:251], v[140:143], v[16:19], v[248:251]
	v_exp_f32_e32 v104, v104
	v_add_f32_e32 v154, v154, v239
	v_mfma_f32_16x16x32_bf16 v[84:87], v[176:179], v[228:231], v[84:87]
	v_exp_f32_e32 v105, v105
	v_add_f32_e32 v154, v154, v104
	v_mfma_f32_16x16x32_bf16 v[92:95], v[180:183], v[228:231], v[92:95]
	v_exp_f32_e32 v106, v106
	v_add_f32_e32 v154, v154, v105
	v_cvt_pk_bf16_f32 v236, v236, v237
	v_mfma_f32_16x16x32_bf16 v[88:91], v[184:187], v[228:231], v[88:91]
	v_exp_f32_e32 v107, v107
	v_add_f32_e32 v154, v154, v106
	v_cvt_pk_bf16_f32 v237, v238, v239
	v_mfma_f32_16x16x32_bf16 v[96:99], v[188:191], v[228:231], v[96:99]
	v_cvt_pk_bf16_f32 v238, v104, v105
	v_cvt_pk_bf16_f32 v239, v106, v107
	v_add_f32_e32 v154, v154, v107
	v_add_f32_e32 v126, v126, v154
	s_waitcnt lgkmcnt(0)
; #define LAS __attribute__((address_space(3)))
; __device__ __forceinline__ s16x4 vtr(const LAS unsigned char* p) { return __builtin_bit_cast(s16x4, __builtin_amdgcn_ds_read_tr16_b64_v4i16((LAS v4i16_t*)p)); }
; __device__ __forceinline__ bf16x8 cat8(s16x4 a, s16x4 b) { return (bf16x8){a[0], a[1], a[2], a[3], b[0], b[1], b[2], b[3]}; }
;     ...
;         for (int kb = 0; kb < 4; ++kb) {
;             const bf16x8 kf0 = *(const LAS bf16x8*)(kb0 + (16 * kb) * 128 + kx0), kf1 = *(const LAS bf16x8*)(kb0 + (16 * kb) * 128 + kx1);
; #pragma unroll
;             for (int gi = 0; gi < GPB; ++gi) { S[gi][kb] = __builtin_amdgcn_mfma_f32_16x16x32_bf16(kf0, qf[GPB * gh + gi][0], cinit, 0, 0, 0);
;                 S[gi][kb] = __builtin_amdgcn_mfma_f32_16x16x32_bf16(kf1, qf[GPB * gh + gi][1], S[gi][kb], 0, 0, 0); } }
;         bf16x8 pf[GPB][2];
; #pragma unroll
;         for (int gi = 0; gi < GPB; ++gi) {
;             if (MASK) {
; #pragma unroll
;                 for (int kb = 0; kb < 4; ++kb)
; #pragma unroll
;                     for (int i = 0; i < 4; ++i) { const int rel = rel0 + 16 * kb + 4 * g + i; S[gi][kb][i] = ((unsigned)(rel + 128) > 256u) ? NEGBIG : S[gi][kb][i]; }
;             }
;             ls[GPB * gh + gi] += exp_step<4>(S[gi]);
;             pf[gi][0] = pack8(S[gi][0], S[gi][1]); pf[gi][1] = pack8(S[gi][2], S[gi][3]);
;         }
; #pragma unroll
;         for (int kc = 0; kc < 2; ++kc)
; #pragma unroll
;             for (int db = 0; db < 4; ++db) {
;                 const LAS unsigned char* va = vrow + ((db ^ swz) << 5) + (32 * kc) * 128;
;                 const bf16x8 vf = cat8(vtr(va), vtr(va + 16 * 128));
; #pragma unroll
;                 for (int gi = 0; gi < GPB; ++gi) O[GPB * gh + gi][db] = __builtin_amdgcn_mfma_f32_16x16x32_bf16(vf, pf[gi][kc], O[GPB * gh + gi][db], 0, 0, 0);
;             }
; __device__ __forceinline__ void na_phase(LAS unsigned char* lds, const bf16_t* Q, const bf16_t* K, const bf16_t* V, bf16_t* Ob, const float* rpb, float negb) {
;     ...
;         for (int t = 0; t < 4; ++t) {
;             dma_tile<2>(lds + ((t + 3) & 3) * NA_BUF, K, V, NA_ROW0(t + 3), DM, dl, w);
;             const LAS unsigned char* buf = lds + (t & 3) * NA_BUF;
;             full_tile<0, 1, 2>(O, ls, qf, negb, buf + hh * 8192, buf + 2 * 8192 + hh * 8192, lane, 0);
;             ring_wait<4>();
	v_mfma_f32_16x16x32_bf16 v[228:231], v[128:131], v[20:23], v[0:3]
	v_exp_f32_e32 v244, v244
	v_exp_f32_e32 v245, v245
	v_mfma_f32_16x16x32_bf16 v[232:235], v[136:139], v[20:23], v[0:3]
	v_exp_f32_e32 v246, v246
	v_add_f32_e32 v154, v244, v245
	v_mfma_f32_16x16x32_bf16 v[228:231], v[132:135], v[24:27], v[228:231]
	v_exp_f32_e32 v247, v247
	v_add_f32_e32 v154, v154, v246
	v_mfma_f32_16x16x32_bf16 v[232:235], v[140:143], v[24:27], v[232:235]
	v_exp_f32_e32 v248, v248
	v_add_f32_e32 v154, v154, v247
	v_mfma_f32_16x16x32_bf16 v[48:51], v[160:163], v[236:239], v[48:51]
	v_exp_f32_e32 v249, v249
	v_add_f32_e32 v154, v154, v248
	v_mfma_f32_16x16x32_bf16 v[44:47], v[164:167], v[236:239], v[44:47]
	v_exp_f32_e32 v250, v250
	v_add_f32_e32 v154, v154, v249
	v_cvt_pk_bf16_f32 v244, v244, v245
	v_mfma_f32_16x16x32_bf16 v[40:43], v[168:171], v[236:239], v[40:43]
	v_exp_f32_e32 v251, v251
	v_add_f32_e32 v154, v154, v250
	v_cvt_pk_bf16_f32 v245, v246, v247
	v_mfma_f32_16x16x32_bf16 v[36:39], v[172:175], v[236:239], v[36:39]
	v_cvt_pk_bf16_f32 v246, v248, v249
	v_cvt_pk_bf16_f32 v247, v250, v251
	v_add_f32_e32 v154, v154, v251
	v_add_f32_e32 v127, v127, v154
	v_mfma_f32_16x16x32_bf16 v[236:239], v[128:131], v[28:31], v[0:3]
	v_exp_f32_e32 v228, v228
	v_exp_f32_e32 v229, v229
	v_mfma_f32_16x16x32_bf16 v[104:107], v[136:139], v[28:31], v[0:3]
	v_exp_f32_e32 v230, v230
	v_add_f32_e32 v154, v228, v229
	v_mfma_f32_16x16x32_bf16 v[236:239], v[132:135], v[32:35], v[236:239]
	v_exp_f32_e32 v231, v231
	v_add_f32_e32 v154, v154, v230
	v_mfma_f32_16x16x32_bf16 v[104:107], v[140:143], v[32:35], v[104:107]
	v_exp_f32_e32 v232, v232
	v_add_f32_e32 v154, v154, v231
	v_mfma_f32_16x16x32_bf16 v[64:67], v[160:163], v[244:247], v[64:67]
	v_exp_f32_e32 v233, v233
	v_add_f32_e32 v154, v154, v232
	v_mfma_f32_16x16x32_bf16 v[60:63], v[164:167], v[244:247], v[60:63]
	v_exp_f32_e32 v234, v234
	v_add_f32_e32 v154, v154, v233
	v_cvt_pk_bf16_f32 v228, v228, v229
	v_mfma_f32_16x16x32_bf16 v[56:59], v[168:171], v[244:247], v[56:59]
	v_exp_f32_e32 v235, v235
	v_add_f32_e32 v154, v154, v234
	v_cvt_pk_bf16_f32 v229, v230, v231
	v_mfma_f32_16x16x32_bf16 v[52:55], v[172:175], v[244:247], v[52:55]
	v_cvt_pk_bf16_f32 v230, v232, v233
	v_cvt_pk_bf16_f32 v231, v234, v235
	v_add_f32_e32 v154, v154, v235
	v_add_f32_e32 v124, v124, v154
	v_mfma_f32_16x16x32_bf16 v[80:83], v[160:163], v[228:231], v[80:83]
	v_exp_f32_e32 v236, v236
	v_exp_f32_e32 v237, v237
	v_exp_f32_e32 v238, v238
	v_add_f32_e32 v154, v236, v237
	v_mfma_f32_16x16x32_bf16 v[76:79], v[164:167], v[228:231], v[76:79]
	v_exp_f32_e32 v239, v239
	v_add_f32_e32 v154, v154, v238
	v_exp_f32_e32 v104, v104
	v_add_f32_e32 v154, v154, v239
	v_mfma_f32_16x16x32_bf16 v[72:75], v[168:171], v[228:231], v[72:75]
	v_exp_f32_e32 v105, v105
	v_add_f32_e32 v154, v154, v104
	v_exp_f32_e32 v106, v106
	v_add_f32_e32 v154, v154, v105
	v_cvt_pk_bf16_f32 v236, v236, v237
	v_mfma_f32_16x16x32_bf16 v[68:71], v[172:175], v[228:231], v[68:71]
	v_exp_f32_e32 v107, v107
	v_add_f32_e32 v154, v154, v106
	v_cvt_pk_bf16_f32 v237, v238, v239
	v_cvt_pk_bf16_f32 v238, v104, v105
	v_cvt_pk_bf16_f32 v239, v106, v107
	v_add_f32_e32 v154, v154, v107
	v_add_f32_e32 v125, v125, v154
	v_mfma_f32_16x16x32_bf16 v[84:87], v[160:163], v[236:239], v[84:87]
	v_mfma_f32_16x16x32_bf16 v[92:95], v[164:167], v[236:239], v[92:95]
	v_mfma_f32_16x16x32_bf16 v[88:91], v[168:171], v[236:239], v[88:91]
	v_mfma_f32_16x16x32_bf16 v[96:99], v[172:175], v[236:239], v[96:99]
	s_add_i32 vcc_lo, vcc_lo, 0x8000
	s_add_u32 s94, s94, 64
	s_addc_u32 s95, s95, 0
	s_add_i32 s96, s96, 1
	s_waitcnt vmcnt(8)
	s_barrier
	s_cmp_lt_i32 s96, s93
	s_cselect_b32 s7, s95, 0
	s_cselect_b32 s6, s94, s82
	s_lshl_b64 s[6:7], s[6:7], 11
	s_add_u32 s76, s67, s6
	s_addc_u32 s77, s4, s7
	s_add_u32 s6, s5, s6
	s_addc_u32 s7, s58, s7
	s_add_i32 s59, s69, vcc_lo
	s_mov_b32 vcc_hi, m0
	s_mov_b32 m0, s59
	s_nop 0
	global_load_lds_dwordx4 v221, s[76:77]
	s_mov_b32 m0, vcc_hi
	s_add_i32 s66, s59, 0x4000
	s_mov_b32 vcc_hi, m0
	s_mov_b32 m0, s66
	s_nop 0
	global_load_lds_dwordx4 v222, s[6:7]
	s_mov_b32 m0, vcc_hi
	s_add_i32 s66, s59, 0x2000
	s_mov_b32 vcc_hi, m0
	s_mov_b32 m0, s66
	s_nop 0
	global_load_lds_dwordx4 v223, s[76:77]
	s_mov_b32 m0, vcc_hi
	s_addk_i32 s59, 0x6000
	s_mov_b32 s66, m0
	s_mov_b32 m0, s59
	s_nop 0
	global_load_lds_dwordx4 v224, s[6:7]
	s_mov_b32 m0, s66
	s_add_i32 s76, s65, vcc_lo
	s_add_i32 s76, s76, 0x8000
	v_add_u32_e32 v144, s76, v111
	v_add3_u32 v193, s76, v210, v205
	v_add_u32_e32 v145, v144, v204
	v_add_u32_e32 v144, v144, v203
	ds_read_b128 v[160:163], v144
	ds_read_b128 v[164:167], v145
	ds_read_b128 v[168:171], v144 offset:2048
	ds_read_b128 v[172:175], v145 offset:2048
	ds_read_b128 v[128:131], v144 offset:4096
	ds_read_b128 v[132:135], v145 offset:4096
	ds_read_b128 v[136:139], v144 offset:6144
	ds_read_b128 v[140:143], v145 offset:6144
	v_add_u32_e32 v158, v193, v206
	v_add_u32_e32 v159, v193, v207
	v_add_u32_e32 v192, v193, v208
	v_add_u32_e32 v193, v193, v209
	s_waitcnt lgkmcnt(4)
; #define LAS __attribute__((address_space(3)))
; __device__ __forceinline__ s16x4 vtr(const LAS unsigned char* p) { return __builtin_bit_cast(s16x4, __builtin_amdgcn_ds_read_tr16_b64_v4i16((LAS v4i16_t*)p)); }
; __device__ __forceinline__ bf16x8 cat8(s16x4 a, s16x4 b) { return (bf16x8){a[0], a[1], a[2], a[3], b[0], b[1], b[2], b[3]}; }
; __device__ __forceinline__ bf16x8 pack8(const f32x4& a, const f32x4& b) { u32x4 w; w.x = pkbf(a[0], a[1]); w.y = pkbf(a[2], a[3]); w.z = pkbf(b[0], b[1]); w.w = pkbf(b[2], b[3]); return __builtin_bit_cast(bf16x8, w); }
;     ...
;     for (int gh = 0; gh < 4 / GPB; ++gh) {
;         f32x4 S[GPB][4];
; #pragma unroll
;         for (int kb = 0; kb < 4; ++kb) {
;             const bf16x8 kf0 = *(const LAS bf16x8*)(kb0 + (16 * kb) * 128 + kx0), kf1 = *(const LAS bf16x8*)(kb0 + (16 * kb) * 128 + kx1);
; #pragma unroll
;             for (int gi = 0; gi < GPB; ++gi) { S[gi][kb] = __builtin_amdgcn_mfma_f32_16x16x32_bf16(kf0, qf[GPB * gh + gi][0], cinit, 0, 0, 0);
;                 S[gi][kb] = __builtin_amdgcn_mfma_f32_16x16x32_bf16(kf1, qf[GPB * gh + gi][1], S[gi][kb], 0, 0, 0); } }
;         bf16x8 pf[GPB][2];
; #pragma unroll
;         for (int gi = 0; gi < GPB; ++gi) {
;             if (MASK) {
; #pragma unroll
;                 for (int kb = 0; kb < 4; ++kb)
; #pragma unroll
;                     for (int i = 0; i < 4; ++i) { const int rel = rel0 + 16 * kb + 4 * g + i; S[gi][kb][i] = ((unsigned)(rel + 128) > 256u) ? NEGBIG : S[gi][kb][i]; }
;             }
;             ls[GPB * gh + gi] += exp_step<4>(S[gi]);
;             pf[gi][0] = pack8(S[gi][0], S[gi][1]); pf[gi][1] = pack8(S[gi][2], S[gi][3]);
;         }
; #pragma unroll
;         for (int kc = 0; kc < 2; ++kc)
; #pragma unroll
;             for (int db = 0; db < 4; ++db) {
;                 const LAS unsigned char* va = vrow + ((db ^ swz) << 5) + (32 * kc) * 128;
;                 const bf16x8 vf = cat8(vtr(va), vtr(va + 16 * 128));
; #pragma unroll
;                 for (int gi = 0; gi < GPB; ++gi) O[GPB * gh + gi][db] = __builtin_amdgcn_mfma_f32_16x16x32_bf16(vf, pf[gi][kc], O[GPB * gh + gi][db], 0, 0, 0);
;             }
	v_mfma_f32_16x16x32_bf16 v[228:231], v[160:163], v[4:7], v[0:3]
	v_mfma_f32_16x16x32_bf16 v[232:235], v[168:171], v[4:7], v[0:3]
	v_mfma_f32_16x16x32_bf16 v[228:231], v[164:167], v[8:11], v[228:231]
	v_mfma_f32_16x16x32_bf16 v[232:235], v[172:175], v[8:11], v[232:235]
	ds_read_b64_tr_b16 v[176:177], v158 offset:16384
	ds_read_b64_tr_b16 v[178:179], v158 offset:18432
	ds_read_b64_tr_b16 v[180:181], v159 offset:16384
	ds_read_b64_tr_b16 v[182:183], v159 offset:18432
	ds_read_b64_tr_b16 v[184:185], v192 offset:16384
	ds_read_b64_tr_b16 v[186:187], v192 offset:18432
	ds_read_b64_tr_b16 v[188:189], v193 offset:16384
	ds_read_b64_tr_b16 v[190:191], v193 offset:18432
	v_mfma_f32_16x16x32_bf16 v[236:239], v[160:163], v[12:15], v[0:3]
	v_exp_f32_e32 v228, v228
	v_exp_f32_e32 v229, v229
	v_exp_f32_e32 v230, v230
	v_add_f32_e32 v154, v228, v229
	v_mfma_f32_16x16x32_bf16 v[104:107], v[168:171], v[12:15], v[0:3]
	v_exp_f32_e32 v231, v231
	v_add_f32_e32 v154, v154, v230
	v_exp_f32_e32 v232, v232
	v_add_f32_e32 v154, v154, v231
	v_mfma_f32_16x16x32_bf16 v[236:239], v[164:167], v[16:19], v[236:239]
	v_exp_f32_e32 v233, v233
	v_add_f32_e32 v154, v154, v232
	v_exp_f32_e32 v234, v234
	v_add_f32_e32 v154, v154, v233
	v_cvt_pk_bf16_f32 v228, v228, v229
	v_mfma_f32_16x16x32_bf16 v[104:107], v[172:175], v[16:19], v[104:107]
	v_exp_f32_e32 v235, v235
	v_add_f32_e32 v154, v154, v234
	v_cvt_pk_bf16_f32 v229, v230, v231
	v_cvt_pk_bf16_f32 v230, v232, v233
	v_cvt_pk_bf16_f32 v231, v234, v235
	v_add_f32_e32 v154, v154, v235
	v_add_f32_e32 v126, v126, v154
	s_waitcnt lgkmcnt(0)
	v_mfma_f32_16x16x32_bf16 v[244:247], v[160:163], v[20:23], v[0:3]
	v_exp_f32_e32 v236, v236
	v_exp_f32_e32 v237, v237
	v_mfma_f32_16x16x32_bf16 v[248:251], v[168:171], v[20:23], v[0:3]
	v_exp_f32_e32 v238, v238
	v_add_f32_e32 v154, v236, v237
	v_mfma_f32_16x16x32_bf16 v[244:247], v[164:167], v[24:27], v[244:247]
	v_exp_f32_e32 v239, v239
	v_add_f32_e32 v154, v154, v238
	v_mfma_f32_16x16x32_bf16 v[248:251], v[172:175], v[24:27], v[248:251]
	v_exp_f32_e32 v104, v104
	v_add_f32_e32 v154, v154, v239
	v_mfma_f32_16x16x32_bf16 v[48:51], v[176:179], v[228:231], v[48:51]
	v_exp_f32_e32 v105, v105
	v_add_f32_e32 v154, v154, v104
	v_mfma_f32_16x16x32_bf16 v[44:47], v[180:183], v[228:231], v[44:47]
	v_exp_f32_e32 v106, v106
	v_add_f32_e32 v154, v154, v105
	v_cvt_pk_bf16_f32 v236, v236, v237
	v_mfma_f32_16x16x32_bf16 v[40:43], v[184:187], v[228:231], v[40:43]
	v_exp_f32_e32 v107, v107
	v_add_f32_e32 v154, v154, v106
	v_cvt_pk_bf16_f32 v237, v238, v239
	v_mfma_f32_16x16x32_bf16 v[36:39], v[188:191], v[228:231], v[36:39]
	v_cvt_pk_bf16_f32 v238, v104, v105
	v_cvt_pk_bf16_f32 v239, v106, v107
	v_add_f32_e32 v154, v154, v107
	v_add_f32_e32 v127, v127, v154
	v_mfma_f32_16x16x32_bf16 v[228:231], v[160:163], v[28:31], v[0:3]
	v_exp_f32_e32 v244, v244
	v_exp_f32_e32 v245, v245
	v_mfma_f32_16x16x32_bf16 v[232:235], v[168:171], v[28:31], v[0:3]
	v_exp_f32_e32 v246, v246
	v_add_f32_e32 v154, v244, v245
	v_mfma_f32_16x16x32_bf16 v[228:231], v[164:167], v[32:35], v[228:231]
	v_exp_f32_e32 v247, v247
	v_add_f32_e32 v154, v154, v246
	v_mfma_f32_16x16x32_bf16 v[232:235], v[172:175], v[32:35], v[232:235]
	v_exp_f32_e32 v248, v248
	v_add_f32_e32 v154, v154, v247
	v_mfma_f32_16x16x32_bf16 v[64:67], v[176:179], v[236:239], v[64:67]
	v_exp_f32_e32 v249, v249
	v_add_f32_e32 v154, v154, v248
	v_mfma_f32_16x16x32_bf16 v[60:63], v[180:183], v[236:239], v[60:63]
	v_exp_f32_e32 v250, v250
	v_add_f32_e32 v154, v154, v249
	v_cvt_pk_bf16_f32 v244, v244, v245
	v_mfma_f32_16x16x32_bf16 v[56:59], v[184:187], v[236:239], v[56:59]
	v_exp_f32_e32 v251, v251
	v_add_f32_e32 v154, v154, v250
	v_cvt_pk_bf16_f32 v245, v246, v247
	v_mfma_f32_16x16x32_bf16 v[52:55], v[188:191], v[236:239], v[52:55]
	v_cvt_pk_bf16_f32 v246, v248, v249
	v_cvt_pk_bf16_f32 v247, v250, v251
	v_add_f32_e32 v154, v154, v251
	v_add_f32_e32 v124, v124, v154
	ds_read_b64_tr_b16 v[160:161], v158 offset:20480
	ds_read_b64_tr_b16 v[162:163], v158 offset:22528
	ds_read_b64_tr_b16 v[164:165], v159 offset:20480
	ds_read_b64_tr_b16 v[166:167], v159 offset:22528
	ds_read_b64_tr_b16 v[168:169], v192 offset:20480
	ds_read_b64_tr_b16 v[170:171], v192 offset:22528
	ds_read_b64_tr_b16 v[172:173], v193 offset:20480
	ds_read_b64_tr_b16 v[174:175], v193 offset:22528
	v_mfma_f32_16x16x32_bf16 v[236:239], v[128:131], v[4:7], v[0:3]
	v_exp_f32_e32 v228, v228
	v_exp_f32_e32 v229, v229
	v_mfma_f32_16x16x32_bf16 v[104:107], v[136:139], v[4:7], v[0:3]
	v_exp_f32_e32 v230, v230
	v_add_f32_e32 v154, v228, v229
	v_mfma_f32_16x16x32_bf16 v[236:239], v[132:135], v[8:11], v[236:239]
	v_exp_f32_e32 v231, v231
	v_add_f32_e32 v154, v154, v230
	v_mfma_f32_16x16x32_bf16 v[104:107], v[140:143], v[8:11], v[104:107]
	v_exp_f32_e32 v232, v232
	v_add_f32_e32 v154, v154, v231
	v_mfma_f32_16x16x32_bf16 v[80:83], v[176:179], v[244:247], v[80:83]
	v_exp_f32_e32 v233, v233
	v_add_f32_e32 v154, v154, v232
	v_mfma_f32_16x16x32_bf16 v[76:79], v[180:183], v[244:247], v[76:79]
	v_exp_f32_e32 v234, v234
	v_add_f32_e32 v154, v154, v233
	v_cvt_pk_bf16_f32 v228, v228, v229
	v_mfma_f32_16x16x32_bf16 v[72:75], v[184:187], v[244:247], v[72:75]
	v_exp_f32_e32 v235, v235
	v_add_f32_e32 v154, v154, v234
	v_cvt_pk_bf16_f32 v229, v230, v231
	v_mfma_f32_16x16x32_bf16 v[68:71], v[188:191], v[244:247], v[68:71]
	v_cvt_pk_bf16_f32 v230, v232, v233
	v_cvt_pk_bf16_f32 v231, v234, v235
	v_add_f32_e32 v154, v154, v235
	v_add_f32_e32 v125, v125, v154
	v_mfma_f32_16x16x32_bf16 v[244:247], v[128:131], v[12:15], v[0:3]
	v_exp_f32_e32 v236, v236
	v_exp_f32_e32 v237, v237
	v_mfma_f32_16x16x32_bf16 v[248:251], v[136:139], v[12:15], v[0:3]
	v_exp_f32_e32 v238, v238
	v_add_f32_e32 v154, v236, v237
	v_mfma_f32_16x16x32_bf16 v[244:247], v[132:135], v[16:19], v[244:247]
	v_exp_f32_e32 v239, v239
	v_add_f32_e32 v154, v154, v238
	v_mfma_f32_16x16x32_bf16 v[248:251], v[140:143], v[16:19], v[248:251]
	v_exp_f32_e32 v104, v104
	v_add_f32_e32 v154, v154, v239
	v_mfma_f32_16x16x32_bf16 v[84:87], v[176:179], v[228:231], v[84:87]
	v_exp_f32_e32 v105, v105
	v_add_f32_e32 v154, v154, v104
	v_mfma_f32_16x16x32_bf16 v[92:95], v[180:183], v[228:231], v[92:95]
	v_exp_f32_e32 v106, v106
	v_add_f32_e32 v154, v154, v105
	v_cvt_pk_bf16_f32 v236, v236, v237
	v_mfma_f32_16x16x32_bf16 v[88:91], v[184:187], v[228:231], v[88:91]
	v_exp_f32_e32 v107, v107
	v_add_f32_e32 v154, v154, v106
	v_cvt_pk_bf16_f32 v237, v238, v239
	v_mfma_f32_16x16x32_bf16 v[96:99], v[188:191], v[228:231], v[96:99]
	v_cvt_pk_bf16_f32 v238, v104, v105
	v_cvt_pk_bf16_f32 v239, v106, v107
	v_add_f32_e32 v154, v154, v107
	v_add_f32_e32 v126, v126, v154
	s_waitcnt lgkmcnt(0)
; #define LAS __attribute__((address_space(3)))
; __device__ __forceinline__ s16x4 vtr(const LAS unsigned char* p) { return __builtin_bit_cast(s16x4, __builtin_amdgcn_ds_read_tr16_b64_v4i16((LAS v4i16_t*)p)); }
; __device__ __forceinline__ bf16x8 cat8(s16x4 a, s16x4 b) { return (bf16x8){a[0], a[1], a[2], a[3], b[0], b[1], b[2], b[3]}; }
;     ...
;         for (int kb = 0; kb < 4; ++kb) {
;             const bf16x8 kf0 = *(const LAS bf16x8*)(kb0 + (16 * kb) * 128 + kx0), kf1 = *(const LAS bf16x8*)(kb0 + (16 * kb) * 128 + kx1);
; #pragma unroll
;             for (int gi = 0; gi < GPB; ++gi) { S[gi][kb] = __builtin_amdgcn_mfma_f32_16x16x32_bf16(kf0, qf[GPB * gh + gi][0], cinit, 0, 0, 0);
;                 S[gi][kb] = __builtin_amdgcn_mfma_f32_16x16x32_bf16(kf1, qf[GPB * gh + gi][1], S[gi][kb], 0, 0, 0); } }
;         bf16x8 pf[GPB][2];
; #pragma unroll
;         for (int gi = 0; gi < GPB; ++gi) {
;             if (MASK) {
; #pragma unroll
;                 for (int kb = 0; kb < 4; ++kb)
; #pragma unroll
;                     for (int i = 0; i < 4; ++i) { const int rel = rel0 + 16 * kb + 4 * g + i; S[gi][kb][i] = ((unsigned)(rel + 128) > 256u) ? NEGBIG : S[gi][kb][i]; }
;             }
;             ls[GPB * gh + gi] += exp_step<4>(S[gi]);
;             pf[gi][0] = pack8(S[gi][0], S[gi][1]); pf[gi][1] = pack8(S[gi][2], S[gi][3]);
;         }
; #pragma unroll
;         for (int kc = 0; kc < 2; ++kc)
; #pragma unroll
;             for (int db = 0; db < 4; ++db) {
;                 const LAS unsigned char* va = vrow + ((db ^ swz) << 5) + (32 * kc) * 128;
;                 const bf16x8 vf = cat8(vtr(va), vtr(va + 16 * 128));
; #pragma unroll
;                 for (int gi = 0; gi < GPB; ++gi) O[GPB * gh + gi][db] = __builtin_amdgcn_mfma_f32_16x16x32_bf16(vf, pf[gi][kc], O[GPB * gh + gi][db], 0, 0, 0);
;             }
; __device__ __forceinline__ void na_phase(LAS unsigned char* lds, const bf16_t* Q, const bf16_t* K, const bf16_t* V, bf16_t* Ob, const float* rpb, float negb) {
;     ...
;         for (int t = 0; t < 4; ++t) {
;             dma_tile<2>(lds + ((t + 3) & 3) * NA_BUF, K, V, NA_ROW0(t + 3), DM, dl, w);
;             const LAS unsigned char* buf = lds + (t & 3) * NA_BUF;
;             full_tile<0, 1, 2>(O, ls, qf, negb, buf + hh * 8192, buf + 2 * 8192 + hh * 8192, lane, 0);
;             ring_wait<4>();
	v_mfma_f32_16x16x32_bf16 v[228:231], v[128:131], v[20:23], v[0:3]
	v_exp_f32_e32 v244, v244
	v_exp_f32_e32 v245, v245
	v_mfma_f32_16x16x32_bf16 v[232:235], v[136:139], v[20:23], v[0:3]
	v_exp_f32_e32 v246, v246
	v_add_f32_e32 v154, v244, v245
	v_mfma_f32_16x16x32_bf16 v[228:231], v[132:135], v[24:27], v[228:231]
	v_exp_f32_e32 v247, v247
	v_add_f32_e32 v154, v154, v246
	v_mfma_f32_16x16x32_bf16 v[232:235], v[140:143], v[24:27], v[232:235]
	v_exp_f32_e32 v248, v248
	v_add_f32_e32 v154, v154, v247
	v_mfma_f32_16x16x32_bf16 v[48:51], v[160:163], v[236:239], v[48:51]
	v_exp_f32_e32 v249, v249
	v_add_f32_e32 v154, v154, v248
	v_mfma_f32_16x16x32_bf16 v[44:47], v[164:167], v[236:239], v[44:47]
	v_exp_f32_e32 v250, v250
	v_add_f32_e32 v154, v154, v249
	v_cvt_pk_bf16_f32 v244, v244, v245
	v_mfma_f32_16x16x32_bf16 v[40:43], v[168:171], v[236:239], v[40:43]
	v_exp_f32_e32 v251, v251
	v_add_f32_e32 v154, v154, v250
	v_cvt_pk_bf16_f32 v245, v246, v247
	v_mfma_f32_16x16x32_bf16 v[36:39], v[172:175], v[236:239], v[36:39]
	v_cvt_pk_bf16_f32 v246, v248, v249
	v_cvt_pk_bf16_f32 v247, v250, v251
	v_add_f32_e32 v154, v154, v251
	v_add_f32_e32 v127, v127, v154
	v_mfma_f32_16x16x32_bf16 v[236:239], v[128:131], v[28:31], v[0:3]
	v_exp_f32_e32 v228, v228
	v_exp_f32_e32 v229, v229
	v_mfma_f32_16x16x32_bf16 v[104:107], v[136:139], v[28:31], v[0:3]
	v_exp_f32_e32 v230, v230
	v_add_f32_e32 v154, v228, v229
	v_mfma_f32_16x16x32_bf16 v[236:239], v[132:135], v[32:35], v[236:239]
	v_exp_f32_e32 v231, v231
	v_add_f32_e32 v154, v154, v230
	v_mfma_f32_16x16x32_bf16 v[104:107], v[140:143], v[32:35], v[104:107]
	v_exp_f32_e32 v232, v232
	v_add_f32_e32 v154, v154, v231
	v_mfma_f32_16x16x32_bf16 v[64:67], v[160:163], v[244:247], v[64:67]
	v_exp_f32_e32 v233, v233
	v_add_f32_e32 v154, v154, v232
	v_mfma_f32_16x16x32_bf16 v[60:63], v[164:167], v[244:247], v[60:63]
	v_exp_f32_e32 v234, v234
	v_add_f32_e32 v154, v154, v233
	v_cvt_pk_bf16_f32 v228, v228, v229
	v_mfma_f32_16x16x32_bf16 v[56:59], v[168:171], v[244:247], v[56:59]
	v_exp_f32_e32 v235, v235
	v_add_f32_e32 v154, v154, v234
	v_cvt_pk_bf16_f32 v229, v230, v231
	v_mfma_f32_16x16x32_bf16 v[52:55], v[172:175], v[244:247], v[52:55]
	v_cvt_pk_bf16_f32 v230, v232, v233
	v_cvt_pk_bf16_f32 v231, v234, v235
	v_add_f32_e32 v154, v154, v235
	v_add_f32_e32 v124, v124, v154
	v_mfma_f32_16x16x32_bf16 v[80:83], v[160:163], v[228:231], v[80:83]
	v_exp_f32_e32 v236, v236
	v_exp_f32_e32 v237, v237
	v_exp_f32_e32 v238, v238
	v_add_f32_e32 v154, v236, v237
	v_mfma_f32_16x16x32_bf16 v[76:79], v[164:167], v[228:231], v[76:79]
	v_exp_f32_e32 v239, v239
	v_add_f32_e32 v154, v154, v238
	v_exp_f32_e32 v104, v104
	v_add_f32_e32 v154, v154, v239
	v_mfma_f32_16x16x32_bf16 v[72:75], v[168:171], v[228:231], v[72:75]
	v_exp_f32_e32 v105, v105
	v_add_f32_e32 v154, v154, v104
	v_exp_f32_e32 v106, v106
	v_add_f32_e32 v154, v154, v105
	v_cvt_pk_bf16_f32 v236, v236, v237
	v_mfma_f32_16x16x32_bf16 v[68:71], v[172:175], v[228:231], v[68:71]
	v_exp_f32_e32 v107, v107
	v_add_f32_e32 v154, v154, v106
	v_cvt_pk_bf16_f32 v237, v238, v239
	v_cvt_pk_bf16_f32 v238, v104, v105
	v_cvt_pk_bf16_f32 v239, v106, v107
	v_add_f32_e32 v154, v154, v107
	v_add_f32_e32 v125, v125, v154
	v_mfma_f32_16x16x32_bf16 v[84:87], v[160:163], v[236:239], v[84:87]
	v_mfma_f32_16x16x32_bf16 v[92:95], v[164:167], v[236:239], v[92:95]
	v_mfma_f32_16x16x32_bf16 v[88:91], v[168:171], v[236:239], v[88:91]
	v_mfma_f32_16x16x32_bf16 v[96:99], v[172:175], v[236:239], v[96:99]
	s_add_i32 vcc_lo, vcc_lo, 0x8000
	s_add_u32 s94, s94, 64
	s_addc_u32 s95, s95, 0
	s_add_i32 s96, s96, 1
	s_waitcnt vmcnt(8)
	s_barrier
	s_cmp_lt_i32 s96, s93
	s_cselect_b32 s7, s95, 0
	s_cselect_b32 s6, s94, s82
	s_lshl_b64 s[6:7], s[6:7], 11
	s_add_u32 s76, s67, s6
	s_addc_u32 s77, s4, s7
	s_add_u32 s6, s5, s6
	s_addc_u32 s7, s58, s7
	s_add_i32 s59, s69, vcc_lo
	s_mov_b32 vcc_hi, m0
	s_mov_b32 m0, s59
	s_nop 0
	global_load_lds_dwordx4 v221, s[76:77]
	s_mov_b32 m0, vcc_hi
	s_add_i32 s66, s59, 0x4000
	s_mov_b32 vcc_hi, m0
	s_mov_b32 m0, s66
	s_nop 0
	global_load_lds_dwordx4 v222, s[6:7]
	s_mov_b32 m0, vcc_hi
	s_add_i32 s66, s59, 0x2000
	s_mov_b32 vcc_hi, m0
	s_mov_b32 m0, s66
	s_nop 0
	global_load_lds_dwordx4 v223, s[76:77]
	s_mov_b32 m0, vcc_hi
	s_addk_i32 s59, 0x6000
	s_mov_b32 s66, m0
	s_mov_b32 m0, s59
	s_nop 0
	global_load_lds_dwordx4 v224, s[6:7]
	s_mov_b32 m0, s66
	s_add_i32 s76, s65, vcc_lo
	s_add_i32 s76, s76, 0x8000
	v_add_u32_e32 v144, s76, v111
	v_add3_u32 v193, s76, v210, v205
	v_add_u32_e32 v145, v144, v204
	v_add_u32_e32 v144, v144, v203
	ds_read_b128 v[160:163], v144
	ds_read_b128 v[164:167], v145
	ds_read_b128 v[168:171], v144 offset:2048
	ds_read_b128 v[172:175], v145 offset:2048
	ds_read_b128 v[128:131], v144 offset:4096
	ds_read_b128 v[132:135], v145 offset:4096
	ds_read_b128 v[136:139], v144 offset:6144
	ds_read_b128 v[140:143], v145 offset:6144
	v_add_u32_e32 v158, v193, v206
	v_add_u32_e32 v159, v193, v207
	v_add_u32_e32 v192, v193, v208
	v_add_u32_e32 v193, v193, v209
	s_waitcnt lgkmcnt(4)
; #define LAS __attribute__((address_space(3)))
; __device__ __forceinline__ s16x4 vtr(const LAS unsigned char* p) { return __builtin_bit_cast(s16x4, __builtin_amdgcn_ds_read_tr16_b64_v4i16((LAS v4i16_t*)p)); }
; __device__ __forceinline__ bf16x8 cat8(s16x4 a, s16x4 b) { return (bf16x8){a[0], a[1], a[2], a[3], b[0], b[1], b[2], b[3]}; }
; __device__ __forceinline__ bf16x8 pack8(const f32x4& a, const f32x4& b) { u32x4 w; w.x = pkbf(a[0], a[1]); w.y = pkbf(a[2], a[3]); w.z = pkbf(b[0], b[1]); w.w = pkbf(b[2], b[3]); return __builtin_bit_cast(bf16x8, w); }
;     ...
;     for (int gh = 0; gh < 4 / GPB; ++gh) {
;         f32x4 S[GPB][4];
; #pragma unroll
;         for (int kb = 0; kb < 4; ++kb) {
;             const bf16x8 kf0 = *(const LAS bf16x8*)(kb0 + (16 * kb) * 128 + kx0), kf1 = *(const LAS bf16x8*)(kb0 + (16 * kb) * 128 + kx1);
; #pragma unroll
;             for (int gi = 0; gi < GPB; ++gi) { S[gi][kb] = __builtin_amdgcn_mfma_f32_16x16x32_bf16(kf0, qf[GPB * gh + gi][0], cinit, 0, 0, 0);
;                 S[gi][kb] = __builtin_amdgcn_mfma_f32_16x16x32_bf16(kf1, qf[GPB * gh + gi][1], S[gi][kb], 0, 0, 0); } }
;         bf16x8 pf[GPB][2];
; #pragma unroll
;         for (int gi = 0; gi < GPB; ++gi) {
;             if (MASK) {
; #pragma unroll
;                 for (int kb = 0; kb < 4; ++kb)
; #pragma unroll
;                     for (int i = 0; i < 4; ++i) { const int rel = rel0 + 16 * kb + 4 * g + i; S[gi][kb][i] = ((unsigned)(rel + 128) > 256u) ? NEGBIG : S[gi][kb][i]; }
;             }
;             ls[GPB * gh + gi] += exp_step<4>(S[gi]);
;             pf[gi][0] = pack8(S[gi][0], S[gi][1]); pf[gi][1] = pack8(S[gi][2], S[gi][3]);
;         }
; #pragma unroll
;         for (int kc = 0; kc < 2; ++kc)
; #pragma unroll
;             for (int db = 0; db < 4; ++db) {
;                 const LAS unsigned char* va = vrow + ((db ^ swz) << 5) + (32 * kc) * 128;
;                 const bf16x8 vf = cat8(vtr(va), vtr(va + 16 * 128));
; #pragma unroll
;                 for (int gi = 0; gi < GPB; ++gi) O[GPB * gh + gi][db] = __builtin_amdgcn_mfma_f32_16x16x32_bf16(vf, pf[gi][kc], O[GPB * gh + gi][db], 0, 0, 0);
;             }
	v_mfma_f32_16x16x32_bf16 v[228:231], v[160:163], v[4:7], v[0:3]
	v_mfma_f32_16x16x32_bf16 v[232:235], v[168:171], v[4:7], v[0:3]
	v_mfma_f32_16x16x32_bf16 v[228:231], v[164:167], v[8:11], v[228:231]
	v_mfma_f32_16x16x32_bf16 v[232:235], v[172:175], v[8:11], v[232:235]
	ds_read_b64_tr_b16 v[176:177], v158 offset:16384
	ds_read_b64_tr_b16 v[178:179], v158 offset:18432
	ds_read_b64_tr_b16 v[180:181], v159 offset:16384
	ds_read_b64_tr_b16 v[182:183], v159 offset:18432
	ds_read_b64_tr_b16 v[184:185], v192 offset:16384
	ds_read_b64_tr_b16 v[186:187], v192 offset:18432
	ds_read_b64_tr_b16 v[188:189], v193 offset:16384
	ds_read_b64_tr_b16 v[190:191], v193 offset:18432
	v_mfma_f32_16x16x32_bf16 v[236:239], v[160:163], v[12:15], v[0:3]
	v_exp_f32_e32 v228, v228
	v_exp_f32_e32 v229, v229
	v_exp_f32_e32 v230, v230
	v_add_f32_e32 v154, v228, v229
	v_mfma_f32_16x16x32_bf16 v[104:107], v[168:171], v[12:15], v[0:3]
	v_exp_f32_e32 v231, v231
	v_add_f32_e32 v154, v154, v230
	v_exp_f32_e32 v232, v232
	v_add_f32_e32 v154, v154, v231
	v_mfma_f32_16x16x32_bf16 v[236:239], v[164:167], v[16:19], v[236:239]
	v_exp_f32_e32 v233, v233
	v_add_f32_e32 v154, v154, v232
	v_exp_f32_e32 v234, v234
	v_add_f32_e32 v154, v154, v233
	v_cvt_pk_bf16_f32 v228, v228, v229
	v_mfma_f32_16x16x32_bf16 v[104:107], v[172:175], v[16:19], v[104:107]
	v_exp_f32_e32 v235, v235
	v_add_f32_e32 v154, v154, v234
	v_cvt_pk_bf16_f32 v229, v230, v231
	v_cvt_pk_bf16_f32 v230, v232, v233
	v_cvt_pk_bf16_f32 v231, v234, v235
	v_add_f32_e32 v154, v154, v235
	v_add_f32_e32 v126, v126, v154
	s_waitcnt lgkmcnt(0)
	v_mfma_f32_16x16x32_bf16 v[244:247], v[160:163], v[20:23], v[0:3]
	v_exp_f32_e32 v236, v236
	v_exp_f32_e32 v237, v237
	v_mfma_f32_16x16x32_bf16 v[248:251], v[168:171], v[20:23], v[0:3]
	v_exp_f32_e32 v238, v238
	v_add_f32_e32 v154, v236, v237
	v_mfma_f32_16x16x32_bf16 v[244:247], v[164:167], v[24:27], v[244:247]
	v_exp_f32_e32 v239, v239
	v_add_f32_e32 v154, v154, v238
	v_mfma_f32_16x16x32_bf16 v[248:251], v[172:175], v[24:27], v[248:251]
	v_exp_f32_e32 v104, v104
	v_add_f32_e32 v154, v154, v239
	v_mfma_f32_16x16x32_bf16 v[48:51], v[176:179], v[228:231], v[48:51]
	v_exp_f32_e32 v105, v105
	v_add_f32_e32 v154, v154, v104
	v_mfma_f32_16x16x32_bf16 v[44:47], v[180:183], v[228:231], v[44:47]
	v_exp_f32_e32 v106, v106
	v_add_f32_e32 v154, v154, v105
	v_cvt_pk_bf16_f32 v236, v236, v237
	v_mfma_f32_16x16x32_bf16 v[40:43], v[184:187], v[228:231], v[40:43]
	v_exp_f32_e32 v107, v107
	v_add_f32_e32 v154, v154, v106
	v_cvt_pk_bf16_f32 v237, v238, v239
	v_mfma_f32_16x16x32_bf16 v[36:39], v[188:191], v[228:231], v[36:39]
	v_cvt_pk_bf16_f32 v238, v104, v105
	v_cvt_pk_bf16_f32 v239, v106, v107
	v_add_f32_e32 v154, v154, v107
	v_add_f32_e32 v127, v127, v154
	v_mfma_f32_16x16x32_bf16 v[228:231], v[160:163], v[28:31], v[0:3]
	v_exp_f32_e32 v244, v244
	v_exp_f32_e32 v245, v245
	v_mfma_f32_16x16x32_bf16 v[232:235], v[168:171], v[28:31], v[0:3]
	v_exp_f32_e32 v246, v246
	v_add_f32_e32 v154, v244, v245
	v_mfma_f32_16x16x32_bf16 v[228:231], v[164:167], v[32:35], v[228:231]
	v_exp_f32_e32 v247, v247
	v_add_f32_e32 v154, v154, v246
	v_mfma_f32_16x16x32_bf16 v[232:235], v[172:175], v[32:35], v[232:235]
	v_exp_f32_e32 v248, v248
	v_add_f32_e32 v154, v154, v247
	v_mfma_f32_16x16x32_bf16 v[64:67], v[176:179], v[236:239], v[64:67]
	v_exp_f32_e32 v249, v249
	v_add_f32_e32 v154, v154, v248
	v_mfma_f32_16x16x32_bf16 v[60:63], v[180:183], v[236:239], v[60:63]
	v_exp_f32_e32 v250, v250
	v_add_f32_e32 v154, v154, v249
	v_cvt_pk_bf16_f32 v244, v244, v245
	v_mfma_f32_16x16x32_bf16 v[56:59], v[184:187], v[236:239], v[56:59]
	v_exp_f32_e32 v251, v251
	v_add_f32_e32 v154, v154, v250
	v_cvt_pk_bf16_f32 v245, v246, v247
	v_mfma_f32_16x16x32_bf16 v[52:55], v[188:191], v[236:239], v[52:55]
	v_cvt_pk_bf16_f32 v246, v248, v249
	v_cvt_pk_bf16_f32 v247, v250, v251
	v_add_f32_e32 v154, v154, v251
	v_add_f32_e32 v124, v124, v154
	ds_read_b64_tr_b16 v[160:161], v158 offset:20480
	ds_read_b64_tr_b16 v[162:163], v158 offset:22528
	ds_read_b64_tr_b16 v[164:165], v159 offset:20480
	ds_read_b64_tr_b16 v[166:167], v159 offset:22528
	ds_read_b64_tr_b16 v[168:169], v192 offset:20480
	ds_read_b64_tr_b16 v[170:171], v192 offset:22528
	ds_read_b64_tr_b16 v[172:173], v193 offset:20480
	ds_read_b64_tr_b16 v[174:175], v193 offset:22528
	v_mfma_f32_16x16x32_bf16 v[236:239], v[128:131], v[4:7], v[0:3]
	v_exp_f32_e32 v228, v228
	v_exp_f32_e32 v229, v229
	v_mfma_f32_16x16x32_bf16 v[104:107], v[136:139], v[4:7], v[0:3]
	v_exp_f32_e32 v230, v230
	v_add_f32_e32 v154, v228, v229
	v_mfma_f32_16x16x32_bf16 v[236:239], v[132:135], v[8:11], v[236:239]
	v_exp_f32_e32 v231, v231
	v_add_f32_e32 v154, v154, v230
	v_mfma_f32_16x16x32_bf16 v[104:107], v[140:143], v[8:11], v[104:107]
	v_exp_f32_e32 v232, v232
	v_add_f32_e32 v154, v154, v231
	v_mfma_f32_16x16x32_bf16 v[80:83], v[176:179], v[244:247], v[80:83]
	v_exp_f32_e32 v233, v233
	v_add_f32_e32 v154, v154, v232
	v_mfma_f32_16x16x32_bf16 v[76:79], v[180:183], v[244:247], v[76:79]
	v_exp_f32_e32 v234, v234
	v_add_f32_e32 v154, v154, v233
	v_cvt_pk_bf16_f32 v228, v228, v229
	v_mfma_f32_16x16x32_bf16 v[72:75], v[184:187], v[244:247], v[72:75]
	v_exp_f32_e32 v235, v235
	v_add_f32_e32 v154, v154, v234
	v_cvt_pk_bf16_f32 v229, v230, v231
	v_mfma_f32_16x16x32_bf16 v[68:71], v[188:191], v[244:247], v[68:71]
	v_cvt_pk_bf16_f32 v230, v232, v233
	v_cvt_pk_bf16_f32 v231, v234, v235
	v_add_f32_e32 v154, v154, v235
	v_add_f32_e32 v125, v125, v154
	v_mfma_f32_16x16x32_bf16 v[244:247], v[128:131], v[12:15], v[0:3]
	v_exp_f32_e32 v236, v236
	v_exp_f32_e32 v237, v237
	v_mfma_f32_16x16x32_bf16 v[248:251], v[136:139], v[12:15], v[0:3]
	v_exp_f32_e32 v238, v238
	v_add_f32_e32 v154, v236, v237
	v_mfma_f32_16x16x32_bf16 v[244:247], v[132:135], v[16:19], v[244:247]
	v_exp_f32_e32 v239, v239
	v_add_f32_e32 v154, v154, v238
	v_mfma_f32_16x16x32_bf16 v[248:251], v[140:143], v[16:19], v[248:251]
	v_exp_f32_e32 v104, v104
	v_add_f32_e32 v154, v154, v239
	v_mfma_f32_16x16x32_bf16 v[84:87], v[176:179], v[228:231], v[84:87]
	v_exp_f32_e32 v105, v105
	v_add_f32_e32 v154, v154, v104
	v_mfma_f32_16x16x32_bf16 v[92:95], v[180:183], v[228:231], v[92:95]
	v_exp_f32_e32 v106, v106
	v_add_f32_e32 v154, v154, v105
	v_cvt_pk_bf16_f32 v236, v236, v237
	v_mfma_f32_16x16x32_bf16 v[88:91], v[184:187], v[228:231], v[88:91]
	v_exp_f32_e32 v107, v107
	v_add_f32_e32 v154, v154, v106
	v_cvt_pk_bf16_f32 v237, v238, v239
	v_mfma_f32_16x16x32_bf16 v[96:99], v[188:191], v[228:231], v[96:99]
	v_cvt_pk_bf16_f32 v238, v104, v105
	v_cvt_pk_bf16_f32 v239, v106, v107
	v_add_f32_e32 v154, v154, v107
	v_add_f32_e32 v126, v126, v154
	s_waitcnt lgkmcnt(0)
; #define LAS __attribute__((address_space(3)))
; __device__ __forceinline__ s16x4 vtr(const LAS unsigned char* p) { return __builtin_bit_cast(s16x4, __builtin_amdgcn_ds_read_tr16_b64_v4i16((LAS v4i16_t*)p)); }
;     ...
;         for (int kb = 0; kb < 4; ++kb) {
;             const bf16x8 kf0 = *(const LAS bf16x8*)(kb0 + (16 * kb) * 128 + kx0), kf1 = *(const LAS bf16x8*)(kb0 + (16 * kb) * 128 + kx1);
; #pragma unroll
;             for (int gi = 0; gi < GPB; ++gi) { S[gi][kb] = __builtin_amdgcn_mfma_f32_16x16x32_bf16(kf0, qf[GPB * gh + gi][0], cinit, 0, 0, 0);
;                 S[gi][kb] = __builtin_amdgcn_mfma_f32_16x16x32_bf16(kf1, qf[GPB * gh + gi][1], S[gi][kb], 0, 0, 0); } }
;         bf16x8 pf[GPB][2];
; #pragma unroll
;         for (int gi = 0; gi < GPB; ++gi) {
;             if (MASK) {
; #pragma unroll
;                 for (int kb = 0; kb < 4; ++kb)
; #pragma unroll
;                     for (int i = 0; i < 4; ++i) { const int rel = rel0 + 16 * kb + 4 * g + i; S[gi][kb][i] = ((unsigned)(rel + 128) > 256u) ? NEGBIG : S[gi][kb][i]; }
;             }
;             ls[GPB * gh + gi] += exp_step<4>(S[gi]);
;             pf[gi][0] = pack8(S[gi][0], S[gi][1]); pf[gi][1] = pack8(S[gi][2], S[gi][3]);
;         }
; #pragma unroll
;         for (int kc = 0; kc < 2; ++kc)
; #pragma unroll
;             for (int db = 0; db < 4; ++db) {
;                 const LAS unsigned char* va = vrow + ((db ^ swz) << 5) + (32 * kc) * 128;
;                 const bf16x8 vf = cat8(vtr(va), vtr(va + 16 * 128));
; #pragma unroll
;                 for (int gi = 0; gi < GPB; ++gi) O[GPB * gh + gi][db] = __builtin_amdgcn_mfma_f32_16x16x32_bf16(vf, pf[gi][kc], O[GPB * gh + gi][db], 0, 0, 0);
;             }
; __device__ __forceinline__ void na_phase(LAS unsigned char* lds, const bf16_t* Q, const bf16_t* K, const bf16_t* V, bf16_t* Ob, const float* rpb, float negb) {
;     ...
;             ring_wait<4>();
;         }
;         for (int t = 4; t < NT; ++t) {
;             dma_tile<2>(lds + ((t + 3) & 3) * NA_BUF, K, V, NA_ROW0(t + 3), DM, dl, w);
;             const LAS unsigned char* buf = lds + (t & 3) * NA_BUF;
;             const int kr = kr_lo + t - 4; const bool rv = kr >= r0w && kr < r0w + 8;
;             if (rv) na_local_tile(O, ls, qf, negb, buf + hh * 8192, buf + 2 * 8192 + hh * 8192, lane, tab + hh * 512 + (kr - r + 7) * 31, true);
	v_mfma_f32_16x16x32_bf16 v[228:231], v[128:131], v[20:23], v[0:3]
	v_exp_f32_e32 v244, v244
	v_exp_f32_e32 v245, v245
	v_mfma_f32_16x16x32_bf16 v[232:235], v[136:139], v[20:23], v[0:3]
	v_exp_f32_e32 v246, v246
	v_add_f32_e32 v154, v244, v245
	v_mfma_f32_16x16x32_bf16 v[228:231], v[132:135], v[24:27], v[228:231]
	v_exp_f32_e32 v247, v247
	v_add_f32_e32 v154, v154, v246
	v_mfma_f32_16x16x32_bf16 v[232:235], v[140:143], v[24:27], v[232:235]
	v_exp_f32_e32 v248, v248
	v_add_f32_e32 v154, v154, v247
	v_mfma_f32_16x16x32_bf16 v[48:51], v[160:163], v[236:239], v[48:51]
	v_exp_f32_e32 v249, v249
	v_add_f32_e32 v154, v154, v248
	v_mfma_f32_16x16x32_bf16 v[44:47], v[164:167], v[236:239], v[44:47]
	v_exp_f32_e32 v250, v250
	v_add_f32_e32 v154, v154, v249
	v_cvt_pk_bf16_f32 v244, v244, v245
	v_mfma_f32_16x16x32_bf16 v[40:43], v[168:171], v[236:239], v[40:43]
	v_exp_f32_e32 v251, v251
	v_add_f32_e32 v154, v154, v250
	v_cvt_pk_bf16_f32 v245, v246, v247
	v_mfma_f32_16x16x32_bf16 v[36:39], v[172:175], v[236:239], v[36:39]
	v_cvt_pk_bf16_f32 v246, v248, v249
	v_cvt_pk_bf16_f32 v247, v250, v251
	v_add_f32_e32 v154, v154, v251
	v_add_f32_e32 v127, v127, v154
	v_mfma_f32_16x16x32_bf16 v[236:239], v[128:131], v[28:31], v[0:3]
	v_exp_f32_e32 v228, v228
	v_exp_f32_e32 v229, v229
	v_mfma_f32_16x16x32_bf16 v[104:107], v[136:139], v[28:31], v[0:3]
	v_exp_f32_e32 v230, v230
	v_add_f32_e32 v154, v228, v229
	v_mfma_f32_16x16x32_bf16 v[236:239], v[132:135], v[32:35], v[236:239]
	v_exp_f32_e32 v231, v231
	v_add_f32_e32 v154, v154, v230
	v_mfma_f32_16x16x32_bf16 v[104:107], v[140:143], v[32:35], v[104:107]
	v_exp_f32_e32 v232, v232
	v_add_f32_e32 v154, v154, v231
	v_mfma_f32_16x16x32_bf16 v[64:67], v[160:163], v[244:247], v[64:67]
	v_exp_f32_e32 v233, v233
	v_add_f32_e32 v154, v154, v232
	v_mfma_f32_16x16x32_bf16 v[60:63], v[164:167], v[244:247], v[60:63]
	v_exp_f32_e32 v234, v234
	v_add_f32_e32 v154, v154, v233
	v_cvt_pk_bf16_f32 v228, v228, v229
	v_mfma_f32_16x16x32_bf16 v[56:59], v[168:171], v[244:247], v[56:59]
	v_exp_f32_e32 v235, v235
	v_add_f32_e32 v154, v154, v234
	v_cvt_pk_bf16_f32 v229, v230, v231
	v_mfma_f32_16x16x32_bf16 v[52:55], v[172:175], v[244:247], v[52:55]
	v_cvt_pk_bf16_f32 v230, v232, v233
	v_cvt_pk_bf16_f32 v231, v234, v235
	v_add_f32_e32 v154, v154, v235
	v_add_f32_e32 v124, v124, v154
	v_mfma_f32_16x16x32_bf16 v[80:83], v[160:163], v[228:231], v[80:83]
	v_exp_f32_e32 v236, v236
	v_exp_f32_e32 v237, v237
	v_exp_f32_e32 v238, v238
	v_add_f32_e32 v154, v236, v237
	v_mfma_f32_16x16x32_bf16 v[76:79], v[164:167], v[228:231], v[76:79]
	v_exp_f32_e32 v239, v239
	v_add_f32_e32 v154, v154, v238
	v_exp_f32_e32 v104, v104
	v_add_f32_e32 v154, v154, v239
	v_mfma_f32_16x16x32_bf16 v[72:75], v[168:171], v[228:231], v[72:75]
	v_exp_f32_e32 v105, v105
	v_add_f32_e32 v154, v154, v104
	v_exp_f32_e32 v106, v106
	v_add_f32_e32 v154, v154, v105
	v_cvt_pk_bf16_f32 v236, v236, v237
	v_mfma_f32_16x16x32_bf16 v[68:71], v[172:175], v[228:231], v[68:71]
	v_exp_f32_e32 v107, v107
	v_add_f32_e32 v154, v154, v106
	v_cvt_pk_bf16_f32 v237, v238, v239
	v_cvt_pk_bf16_f32 v238, v104, v105
	v_cvt_pk_bf16_f32 v239, v106, v107
	v_add_f32_e32 v154, v154, v107
	v_add_f32_e32 v125, v125, v154
	v_mfma_f32_16x16x32_bf16 v[84:87], v[160:163], v[236:239], v[84:87]
	v_mfma_f32_16x16x32_bf16 v[92:95], v[164:167], v[236:239], v[92:95]
	v_mfma_f32_16x16x32_bf16 v[88:91], v[168:171], v[236:239], v[88:91]
	v_mfma_f32_16x16x32_bf16 v[96:99], v[172:175], v[236:239], v[96:99]
	s_add_i32 vcc_lo, vcc_lo, 0x8000
	s_add_u32 s94, s94, 64
	s_addc_u32 s95, s95, 0
	s_add_i32 s96, s96, 1
	s_waitcnt vmcnt(8)
	s_barrier
	s_cmp_lt_i32 s93, 5
	s_cbranch_scc1 .LBB0_361
	s_add_i32 s97, s97, -4
	s_min_u32 s94, s97, 0x78
	s_add_i32 s95, s94, 8
	s_add_i32 s96, s93, -4
	s_cmp_gt_u32 s68, 4
	s_cselect_b32 s7, 0, 0
	s_cselect_b32 s6, s68, 4
	s_lshl_b64 s[6:7], s[6:7], 6
	s_add_u32 s6, s6, s61
	s_addc_u32 s7, s7, 0
	s_add_u32 s59, s6, 0xffffffc0
	s_addc_u32 s66, s7, -1
	s_add_i32 s7, s2, s68
	s_mul_i32 s6, s60, 0x7c
	s_mulk_i32 s7, 0x7c
	s_sub_i32 s6, s6, s7
	s_mov_b32 s97, 0
	v_add_u32_e32 v128, s6, v219
	s_add_i32 s68, s60, -4
	v_add_u32_e32 v129, s6, v220
	s_mov_b32 s6, 0x20000
	s_branch .LBB0_383
